# speedup vs baseline: 1.0104x; 1.0104x over previous
; DEVINL float shx(float v, int m, int lane) { return __int_as_float(__builtin_amdgcn_ds_bpermute((lane ^ m) << 2, __float_as_int(v))); }
; DEVINL void phase_gemm_res(const Params& p, const u16* A, int lda, const u16* B, int K, const float* resid, char* smem, int wv) {
;     ...
; #pragma unroll
;     for (int ai = 0; ai < 2; ++ai)
; #pragma unroll
;       for (int m = 0; m < 4; ++m) {
;         int row = m0 + ai * 128 + wr * 64 + m * 16 + fr;
;         size_t off = (size_t)row * DM + n0 + wc * 32 + fq * 4;
;         size_t offw = (size_t)row * DM + n0 + wc * 32 + (fq & 1) * 16 + (fq >> 1) * 8;
;         float ss = 0.f;
; #pragma unroll
;         for (int bj = 0; bj < 2; ++bj) {
;           f32x4 vv[2];
; #pragma unroll
;           for (int n = 0; n < 2; ++n) {
;             float4 rv = *(const float4*)(resid + off + bj * 128 + n * 16);
;             f32x4 v = acc[ai][bj][m][n];
;             v[0] += rv.x; v[1] += rv.y; v[2] += rv.z; v[3] += rv.w;
;             float4 ov; ov.x = v[0]; ov.y = v[1]; ov.z = v[2]; ov.w = v[3];
;             *(float4*)(out + off + bj * 128 + n * 16) = ov;
;             ss += sumsq4(v);
;             vv[n] = v;
;           }
;           *(u32x4*)(xb + offw + bj * 128) = widen2(vv[0], vv[1]);
;         }
;         ss += shx(ss, 16, lane); ss += shx(ss, 32, lane);
;         if (fq == 0) part[(size_t)row * 32 + pn * 4 + wc] = ss;
;       }
.LBB0_854:
	s_ashr_i32 s0, s31, 2
	s_andn2_b32 s0, s0, 63
	v_or_b32_e32 v128, s0, v128
	s_bfe_u32 s29, s31, 0x20006
	v_add_u32_e32 v130, s28, v128
	s_lshl_b32 s0, s29, 5
	v_ashrrev_i32_e32 v131, 31, v130
	s_or_b32 s24, s24, s0
	v_lshrrev_b32_e32 v128, 2, v151
	v_lshlrev_b64 v[134:135], 11, v[130:131]
	v_and_b32_e32 v132, 12, v128
	v_lshl_add_u64 v[142:143], v[134:135], 0, s[24:25]
	v_or_b32_e32 v134, v142, v132
	v_mov_b32_e32 v135, v143
	v_readlane_b32 s40, v254, 2
	v_lshlrev_b64 v[138:139], 2, v[134:135]
	v_readlane_b32 s41, v254, 3
	v_lshl_add_u64 v[148:149], s[92:93], 0, v[138:139]
	s_lshl_b32 s0, s30, 2
	v_lshl_add_u64 v[146:147], s[40:41], 0, v[138:139]
	global_load_dwordx4 v[200:203], v[146:147], off
	global_load_dwordx4 v[204:207], v[146:147], off offset:64
	global_load_dwordx4 v[208:211], v[146:147], off offset:512
	global_load_dwordx4 v[212:215], v[146:147], off offset:576
	s_ashr_i32 s1, s0, 31
	s_lshl_b64 s[0:1], s[0:1], 2
	s_add_u32 s0, s60, s0
	s_addc_u32 s1, s61, s1
	s_lshl_b32 s28, s29, 2
	s_add_u32 s28, s0, s28
	s_addc_u32 s29, s1, 0
	v_readlane_b32 s42, v254, 4
	v_readlane_b32 s43, v254, 5
	v_readlane_b32 s44, v254, 6
	v_readlane_b32 s45, v254, 7
	v_readlane_b32 s46, v254, 8
	v_readlane_b32 s47, v254, 9
	v_readlane_b32 s48, v254, 10
	v_readlane_b32 s49, v254, 11
	v_readlane_b32 s50, v254, 12
	v_readlane_b32 s51, v254, 13
	v_readlane_b32 s52, v254, 14
	v_readlane_b32 s53, v254, 15
	v_readlane_b32 s54, v254, 16
	v_readlane_b32 s55, v254, 17
	s_waitcnt vmcnt(3)
	v_pk_add_f32 v[134:135], v[124:125], v[200:201]
	v_pk_add_f32 v[136:137], v[126:127], v[202:203]
	global_store_dwordx4 v[148:149], v[134:137], off
	v_and_b32_e32 v124, 16, v151
	v_and_or_b32 v124, v128, 8, v124
	v_lshlrev_b32_e32 v128, 1, v124
	v_lshl_add_u64 v[124:125], s[90:91], 0, v[128:129]
	v_lshl_add_u64 v[126:127], v[142:143], 1, v[124:125]
	v_cvt_pk_bf16_f32 v142, v134, v135
	v_cvt_pk_bf16_f32 v143, v136, v137
	s_waitcnt vmcnt(3)
	v_pk_add_f32 v[138:139], v[116:117], v[204:205]
	v_pk_add_f32 v[140:141], v[118:119], v[206:207]
	v_cvt_pk_bf16_f32 v144, v138, v139
	v_cvt_pk_bf16_f32 v145, v140, v141
	s_nop 0
	v_permlane16_swap_b32_e32 v142, v144
	v_permlane16_swap_b32_e32 v143, v145
	global_store_dwordx4 v[148:149], v[138:141], off offset:64
	global_store_dwordx4 v[126:127], v[142:145], off
	s_waitcnt vmcnt(4)
	v_pk_add_f32 v[120:121], v[120:121], v[208:209]
	v_pk_add_f32 v[122:123], v[122:123], v[210:211]
	global_store_dwordx4 v[148:149], v[120:123], off offset:512
	v_and_b32_e32 v116, 63, v151
	v_lshlrev_b32_e32 v118, 2, v116
	v_cmp_gt_u32_e32 vcc, 16, v116
	v_xor_b32_e32 v117, 64, v118
	v_xor_b32_e32 v116, 0x80, v118
	v_pk_mul_f32 v[118:119], v[134:135], v[134:135]
	v_pk_mul_f32 v[134:135], v[136:137], v[136:137]
	v_add_f32_e32 v118, v118, v119
	v_add_f32_e32 v118, v134, v118
	v_add_f32_e32 v128, v135, v118
	v_pk_mul_f32 v[118:119], v[138:139], v[138:139]
	v_pk_mul_f32 v[134:135], v[140:141], v[140:141]
	v_add_f32_e32 v118, v118, v119
	v_add_f32_e32 v118, v134, v118
	v_add_f32_e32 v118, v135, v118
	v_pk_mul_f32 v[134:135], v[120:121], v[120:121]
	v_add_f32_e32 v119, v128, v118
	v_pk_mul_f32 v[136:137], v[122:123], v[122:123]
	v_cvt_pk_bf16_f32 v118, v120, v121
	v_add_f32_e32 v120, v134, v135
	v_add_f32_e32 v120, v136, v120
	v_add_f32_e32 v120, v137, v120
	v_add_f32_e32 v119, v119, v120
	s_waitcnt vmcnt(4)
	v_pk_add_f32 v[112:113], v[112:113], v[212:213]
	v_pk_add_f32 v[114:115], v[114:115], v[214:215]
	v_pk_mul_f32 v[120:121], v[112:113], v[112:113]
	v_pk_mul_f32 v[134:135], v[114:115], v[114:115]
	v_add_f32_e32 v120, v120, v121
	v_add_f32_e32 v120, v134, v120
	v_add_f32_e32 v120, v135, v120
	v_add_f32_e32 v128, v119, v120
	ds_bpermute_b32 v133, v117, v128
	global_store_dwordx4 v[148:149], v[112:115], off offset:576
	v_cvt_pk_bf16_f32 v120, v112, v113
	v_cvt_pk_bf16_f32 v119, v122, v123
	v_cvt_pk_bf16_f32 v121, v114, v115
	s_waitcnt lgkmcnt(0)
	v_add_f32_e32 v112, v128, v133
	ds_bpermute_b32 v113, v116, v112
	v_permlane16_swap_b32_e32 v118, v120
	v_permlane16_swap_b32_e32 v119, v121
	global_store_dwordx4 v[126:127], v[118:121], off offset:256
	s_and_saveexec_b64 s[30:31], vcc
	s_cbranch_execz .LBB0_856
	v_lshlrev_b64 v[114:115], 7, v[130:131]
	v_lshl_add_u64 v[114:115], s[28:29], 0, v[114:115]
	s_waitcnt lgkmcnt(0)
	v_add_f32_e32 v112, v112, v113
	global_store_dword v[114:115], v112, off
; DEVINL float shx(float v, int m, int lane) { return __int_as_float(__builtin_amdgcn_ds_bpermute((lane ^ m) << 2, __float_as_int(v))); }
; DEVINL void phase_gemm_res(const Params& p, const u16* A, int lda, const u16* B, int K, const float* resid, char* smem, int wv) {
;     ...
; #pragma unroll
;     for (int ai = 0; ai < 2; ++ai)
; #pragma unroll
;       for (int m = 0; m < 4; ++m) {
;         int row = m0 + ai * 128 + wr * 64 + m * 16 + fr;
;         size_t off = (size_t)row * DM + n0 + wc * 32 + fq * 4;
;         size_t offw = (size_t)row * DM + n0 + wc * 32 + (fq & 1) * 16 + (fq >> 1) * 8;
;         float ss = 0.f;
; #pragma unroll
;         for (int bj = 0; bj < 2; ++bj) {
;           f32x4 vv[2];
; #pragma unroll
;           for (int n = 0; n < 2; ++n) {
;             float4 rv = *(const float4*)(resid + off + bj * 128 + n * 16);
;             f32x4 v = acc[ai][bj][m][n];
;             v[0] += rv.x; v[1] += rv.y; v[2] += rv.z; v[3] += rv.w;
;             float4 ov; ov.x = v[0]; ov.y = v[1]; ov.z = v[2]; ov.w = v[3];
;             *(float4*)(out + off + bj * 128 + n * 16) = ov;
;             ss += sumsq4(v);
;             vv[n] = v;
;           }
;           *(u32x4*)(xb + offw + bj * 128) = widen2(vv[0], vv[1]);
;         }
;         ss += shx(ss, 16, lane); ss += shx(ss, 32, lane);
;         if (fq == 0) part[(size_t)row * 32 + pn * 4 + wc] = ss;
;       }
.LBB0_856:
	s_or_b64 exec, exec, s[30:31]
	v_or_b32_e32 v112, 16, v130
	s_waitcnt lgkmcnt(0)
	v_ashrrev_i32_e32 v113, 31, v112
	v_lshlrev_b64 v[114:115], 11, v[112:113]
	v_lshl_add_u64 v[114:115], v[114:115], 0, s[24:25]
	v_or_b32_e32 v118, v114, v132
	v_mov_b32_e32 v119, v115
	v_readlane_b32 s40, v254, 2
	v_lshlrev_b64 v[122:123], 2, v[118:119]
	v_readlane_b32 s41, v254, 3
	v_lshl_add_u64 v[114:115], v[114:115], 1, v[124:125]
	v_readlane_b32 s42, v254, 4
	v_lshl_add_u64 v[126:127], s[40:41], 0, v[122:123]
	global_load_dwordx4 v[200:203], v[126:127], off
	global_load_dwordx4 v[204:207], v[126:127], off offset:64
	global_load_dwordx4 v[208:211], v[126:127], off offset:512
	global_load_dwordx4 v[212:215], v[126:127], off offset:576
	v_lshl_add_u64 v[122:123], s[92:93], 0, v[122:123]
	v_readlane_b32 s43, v254, 5
	v_readlane_b32 s44, v254, 6
	v_readlane_b32 s45, v254, 7
	v_readlane_b32 s46, v254, 8
	v_readlane_b32 s47, v254, 9
	v_readlane_b32 s48, v254, 10
	v_readlane_b32 s49, v254, 11
	v_readlane_b32 s50, v254, 12
	v_readlane_b32 s51, v254, 13
	v_readlane_b32 s52, v254, 14
	v_readlane_b32 s53, v254, 15
	v_readlane_b32 s54, v254, 16
	v_readlane_b32 s55, v254, 17
	s_waitcnt vmcnt(3)
	v_pk_add_f32 v[108:109], v[108:109], v[200:201]
	v_pk_add_f32 v[110:111], v[110:111], v[202:203]
	global_store_dwordx4 v[122:123], v[108:111], off
	v_cvt_pk_bf16_f32 v134, v108, v109
	v_cvt_pk_bf16_f32 v135, v110, v111
	v_pk_mul_f32 v[108:109], v[108:109], v[108:109]
	v_pk_mul_f32 v[110:111], v[110:111], v[110:111]
	v_add_f32_e32 v108, v108, v109
	v_add_f32_e32 v108, v110, v108
	v_add_f32_e32 v108, v111, v108
	s_waitcnt vmcnt(3)
	v_pk_add_f32 v[100:101], v[100:101], v[204:205]
	v_pk_add_f32 v[102:103], v[102:103], v[206:207]
	v_cvt_pk_bf16_f32 v136, v100, v101
	v_cvt_pk_bf16_f32 v137, v102, v103
	s_nop 0
	v_permlane16_swap_b32_e32 v134, v136
	v_permlane16_swap_b32_e32 v135, v137
	global_store_dwordx4 v[122:123], v[100:103], off offset:64
	global_store_dwordx4 v[114:115], v[134:137], off
	s_nop 0
	v_pk_mul_f32 v[100:101], v[100:101], v[100:101]
	v_pk_mul_f32 v[102:103], v[102:103], v[102:103]
	v_add_f32_e32 v100, v100, v101
	v_add_f32_e32 v100, v102, v100
	v_add_f32_e32 v100, v103, v100
	v_add_f32_e32 v101, v108, v100
	s_waitcnt vmcnt(4)
	v_pk_add_f32 v[104:105], v[104:105], v[208:209]
	v_pk_add_f32 v[106:107], v[106:107], v[210:211]
	global_store_dwordx4 v[122:123], v[104:107], off offset:512
	v_pk_mul_f32 v[102:103], v[104:105], v[104:105]
	v_pk_mul_f32 v[108:109], v[106:107], v[106:107]
	v_add_f32_e32 v102, v102, v103
	v_add_f32_e32 v102, v108, v102
	v_add_f32_e32 v102, v109, v102
	v_add_f32_e32 v101, v101, v102
	v_cvt_pk_bf16_f32 v100, v104, v105
	s_waitcnt vmcnt(4)
	v_pk_add_f32 v[96:97], v[96:97], v[212:213]
	v_pk_add_f32 v[98:99], v[98:99], v[214:215]
	v_pk_mul_f32 v[102:103], v[96:97], v[96:97]
	v_pk_mul_f32 v[104:105], v[98:99], v[98:99]
	v_add_f32_e32 v102, v102, v103
	v_add_f32_e32 v102, v104, v102
	v_add_f32_e32 v102, v105, v102
	v_add_f32_e32 v104, v101, v102
	ds_bpermute_b32 v105, v117, v104
	global_store_dwordx4 v[122:123], v[96:99], off offset:576
	v_cvt_pk_bf16_f32 v102, v96, v97
	v_cvt_pk_bf16_f32 v101, v106, v107
	v_cvt_pk_bf16_f32 v103, v98, v99
	s_waitcnt lgkmcnt(0)
	v_add_f32_e32 v96, v104, v105
	ds_bpermute_b32 v97, v116, v96
	v_permlane16_swap_b32_e32 v100, v102
	v_permlane16_swap_b32_e32 v101, v103
	global_store_dwordx4 v[114:115], v[100:103], off offset:256
	s_and_saveexec_b64 s[30:31], vcc
	s_cbranch_execz .LBB0_858
	v_lshlrev_b64 v[98:99], 7, v[112:113]
	v_lshl_add_u64 v[98:99], s[28:29], 0, v[98:99]
	s_waitcnt lgkmcnt(0)
	v_add_f32_e32 v96, v96, v97
	global_store_dword v[98:99], v96, off
.LBB0_858:
	s_or_b64 exec, exec, s[30:31]
	v_or_b32_e32 v96, 32, v130
	s_waitcnt lgkmcnt(0)
	v_ashrrev_i32_e32 v97, 31, v96
	v_lshlrev_b64 v[98:99], 11, v[96:97]
	v_lshl_add_u64 v[102:103], v[98:99], 0, s[24:25]
	v_or_b32_e32 v98, v102, v132
	v_mov_b32_e32 v99, v103
	v_readlane_b32 s40, v254, 2
	v_lshlrev_b64 v[104:105], 2, v[98:99]
	v_readlane_b32 s41, v254, 3
	v_lshl_add_u64 v[108:109], s[92:93], 0, v[104:105]
	v_lshl_add_u64 v[110:111], v[102:103], 1, v[124:125]
	v_lshl_add_u64 v[106:107], s[40:41], 0, v[104:105]
	global_load_dwordx4 v[200:203], v[106:107], off
	global_load_dwordx4 v[204:207], v[106:107], off offset:64
	global_load_dwordx4 v[208:211], v[106:107], off offset:512
	global_load_dwordx4 v[212:215], v[106:107], off offset:576
	v_readlane_b32 s42, v254, 4
	v_readlane_b32 s43, v254, 5
	v_readlane_b32 s44, v254, 6
	v_readlane_b32 s45, v254, 7
	v_readlane_b32 s46, v254, 8
	v_readlane_b32 s47, v254, 9
	v_readlane_b32 s48, v254, 10
	v_readlane_b32 s49, v254, 11
	v_readlane_b32 s50, v254, 12
	v_readlane_b32 s51, v254, 13
	v_readlane_b32 s52, v254, 14
	v_readlane_b32 s53, v254, 15
	v_readlane_b32 s54, v254, 16
	v_readlane_b32 s55, v254, 17
	s_waitcnt vmcnt(3)
	v_pk_add_f32 v[92:93], v[92:93], v[200:201]
	v_pk_add_f32 v[94:95], v[94:95], v[202:203]
	global_store_dwordx4 v[108:109], v[92:95], off
	v_cvt_pk_bf16_f32 v102, v92, v93
	v_cvt_pk_bf16_f32 v103, v94, v95
	v_pk_mul_f32 v[92:93], v[92:93], v[92:93]
	v_pk_mul_f32 v[94:95], v[94:95], v[94:95]
	v_add_f32_e32 v92, v92, v93
	v_add_f32_e32 v92, v94, v92
	v_add_f32_e32 v92, v95, v92
	s_waitcnt vmcnt(3)
	v_pk_add_f32 v[84:85], v[84:85], v[204:205]
	v_pk_add_f32 v[86:87], v[86:87], v[206:207]
	v_cvt_pk_bf16_f32 v104, v84, v85
	v_cvt_pk_bf16_f32 v105, v86, v87
	s_nop 0
	v_permlane16_swap_b32_e32 v102, v104
	v_permlane16_swap_b32_e32 v103, v105
	global_store_dwordx4 v[108:109], v[84:87], off offset:64
	global_store_dwordx4 v[110:111], v[102:105], off
	s_nop 0
	v_pk_mul_f32 v[84:85], v[84:85], v[84:85]
	v_pk_mul_f32 v[86:87], v[86:87], v[86:87]
	v_add_f32_e32 v84, v84, v85
	v_add_f32_e32 v84, v86, v84
	v_add_f32_e32 v84, v87, v84
	v_add_f32_e32 v85, v92, v84
	s_waitcnt vmcnt(4)
	v_pk_add_f32 v[88:89], v[88:89], v[208:209]
	v_pk_add_f32 v[90:91], v[90:91], v[210:211]
	global_store_dwordx4 v[108:109], v[88:91], off offset:512
	v_pk_mul_f32 v[86:87], v[88:89], v[88:89]
	v_pk_mul_f32 v[92:93], v[90:91], v[90:91]
	v_add_f32_e32 v86, v86, v87
	v_add_f32_e32 v86, v92, v86
	v_add_f32_e32 v86, v93, v86
	v_add_f32_e32 v85, v85, v86
	v_cvt_pk_bf16_f32 v84, v88, v89
	s_waitcnt vmcnt(4)
	v_pk_add_f32 v[80:81], v[80:81], v[212:213]
	v_pk_add_f32 v[82:83], v[82:83], v[214:215]
	v_pk_mul_f32 v[86:87], v[80:81], v[80:81]
	v_pk_mul_f32 v[88:89], v[82:83], v[82:83]
	v_add_f32_e32 v86, v86, v87
	v_add_f32_e32 v86, v88, v86
	v_add_f32_e32 v86, v89, v86
	v_add_f32_e32 v88, v85, v86
	ds_bpermute_b32 v89, v117, v88
	global_store_dwordx4 v[108:109], v[80:83], off offset:576
	v_cvt_pk_bf16_f32 v86, v80, v81
	v_cvt_pk_bf16_f32 v85, v90, v91
	v_cvt_pk_bf16_f32 v87, v82, v83
	s_waitcnt lgkmcnt(0)
	v_add_f32_e32 v80, v88, v89
	ds_bpermute_b32 v81, v116, v80
	v_permlane16_swap_b32_e32 v84, v86
	v_permlane16_swap_b32_e32 v85, v87
	global_store_dwordx4 v[110:111], v[84:87], off offset:256
	s_and_saveexec_b64 s[30:31], vcc
	s_cbranch_execz .LBB0_860
; DEVINL float shx(float v, int m, int lane) { return __int_as_float(__builtin_amdgcn_ds_bpermute((lane ^ m) << 2, __float_as_int(v))); }
; DEVINL void phase_gemm_res(const Params& p, const u16* A, int lda, const u16* B, int K, const float* resid, char* smem, int wv) {
;     ...
; #pragma unroll
;     for (int ai = 0; ai < 2; ++ai)
; #pragma unroll
;       for (int m = 0; m < 4; ++m) {
;         int row = m0 + ai * 128 + wr * 64 + m * 16 + fr;
;         size_t off = (size_t)row * DM + n0 + wc * 32 + fq * 4;
;         size_t offw = (size_t)row * DM + n0 + wc * 32 + (fq & 1) * 16 + (fq >> 1) * 8;
;         float ss = 0.f;
; #pragma unroll
;         for (int bj = 0; bj < 2; ++bj) {
;           f32x4 vv[2];
; #pragma unroll
;           for (int n = 0; n < 2; ++n) {
;             float4 rv = *(const float4*)(resid + off + bj * 128 + n * 16);
;             f32x4 v = acc[ai][bj][m][n];
;             v[0] += rv.x; v[1] += rv.y; v[2] += rv.z; v[3] += rv.w;
;             float4 ov; ov.x = v[0]; ov.y = v[1]; ov.z = v[2]; ov.w = v[3];
;             *(float4*)(out + off + bj * 128 + n * 16) = ov;
;             ss += sumsq4(v);
;             vv[n] = v;
;           }
;           *(u32x4*)(xb + offw + bj * 128) = widen2(vv[0], vv[1]);
;         }
;         ss += shx(ss, 16, lane); ss += shx(ss, 32, lane);
;         if (fq == 0) part[(size_t)row * 32 + pn * 4 + wc] = ss;
;       }
	v_lshlrev_b64 v[82:83], 7, v[96:97]
	v_lshl_add_u64 v[82:83], s[28:29], 0, v[82:83]
	s_waitcnt lgkmcnt(0)
	v_add_f32_e32 v80, v80, v81
	global_store_dword v[82:83], v80, off
.LBB0_860:
	s_or_b64 exec, exec, s[30:31]
	v_or_b32_e32 v80, 48, v130
	s_waitcnt lgkmcnt(0)
	v_ashrrev_i32_e32 v81, 31, v80
	v_lshlrev_b64 v[82:83], 11, v[80:81]
	v_lshl_add_u64 v[86:87], v[82:83], 0, s[24:25]
	v_or_b32_e32 v82, v86, v132
	v_mov_b32_e32 v83, v87
	v_readlane_b32 s40, v254, 2
	v_lshlrev_b64 v[88:89], 2, v[82:83]
	v_readlane_b32 s41, v254, 3
	v_lshl_add_u64 v[92:93], s[92:93], 0, v[88:89]
	v_lshl_add_u64 v[94:95], v[86:87], 1, v[124:125]
	v_lshl_add_u64 v[90:91], s[40:41], 0, v[88:89]
	global_load_dwordx4 v[200:203], v[90:91], off
	global_load_dwordx4 v[204:207], v[90:91], off offset:64
	global_load_dwordx4 v[208:211], v[90:91], off offset:512
	global_load_dwordx4 v[212:215], v[90:91], off offset:576
	v_readlane_b32 s42, v254, 4
	v_readlane_b32 s43, v254, 5
	v_readlane_b32 s44, v254, 6
	v_readlane_b32 s45, v254, 7
	v_readlane_b32 s46, v254, 8
	v_readlane_b32 s47, v254, 9
	v_readlane_b32 s48, v254, 10
	v_readlane_b32 s49, v254, 11
	v_readlane_b32 s50, v254, 12
	v_readlane_b32 s51, v254, 13
	v_readlane_b32 s52, v254, 14
	v_readlane_b32 s53, v254, 15
	v_readlane_b32 s54, v254, 16
	v_readlane_b32 s55, v254, 17
	s_waitcnt vmcnt(3)
	v_pk_add_f32 v[76:77], v[76:77], v[200:201]
	v_pk_add_f32 v[78:79], v[78:79], v[202:203]
	global_store_dwordx4 v[92:93], v[76:79], off
	v_cvt_pk_bf16_f32 v86, v76, v77
	v_cvt_pk_bf16_f32 v87, v78, v79
	v_pk_mul_f32 v[76:77], v[76:77], v[76:77]
	v_pk_mul_f32 v[78:79], v[78:79], v[78:79]
	v_add_f32_e32 v76, v76, v77
	v_add_f32_e32 v76, v78, v76
	v_add_f32_e32 v76, v79, v76
	s_waitcnt vmcnt(3)
	v_pk_add_f32 v[68:69], v[68:69], v[204:205]
	v_pk_add_f32 v[70:71], v[70:71], v[206:207]
	v_cvt_pk_bf16_f32 v88, v68, v69
	v_cvt_pk_bf16_f32 v89, v70, v71
	s_nop 0
	v_permlane16_swap_b32_e32 v86, v88
	v_permlane16_swap_b32_e32 v87, v89
	global_store_dwordx4 v[92:93], v[68:71], off offset:64
	global_store_dwordx4 v[94:95], v[86:89], off
	s_nop 0
	v_pk_mul_f32 v[68:69], v[68:69], v[68:69]
	v_pk_mul_f32 v[70:71], v[70:71], v[70:71]
	v_add_f32_e32 v68, v68, v69
	v_add_f32_e32 v68, v70, v68
	v_add_f32_e32 v68, v71, v68
	v_add_f32_e32 v69, v76, v68
	s_waitcnt vmcnt(4)
	v_pk_add_f32 v[72:73], v[72:73], v[208:209]
	v_pk_add_f32 v[74:75], v[74:75], v[210:211]
	global_store_dwordx4 v[92:93], v[72:75], off offset:512
	v_pk_mul_f32 v[70:71], v[72:73], v[72:73]
	v_pk_mul_f32 v[76:77], v[74:75], v[74:75]
	v_add_f32_e32 v70, v70, v71
	v_add_f32_e32 v70, v76, v70
	v_add_f32_e32 v70, v77, v70
	v_add_f32_e32 v69, v69, v70
	v_cvt_pk_bf16_f32 v68, v72, v73
	s_waitcnt vmcnt(4)
	v_pk_add_f32 v[64:65], v[64:65], v[212:213]
	v_pk_add_f32 v[66:67], v[66:67], v[214:215]
	v_pk_mul_f32 v[70:71], v[64:65], v[64:65]
	v_pk_mul_f32 v[72:73], v[66:67], v[66:67]
	v_add_f32_e32 v70, v70, v71
	v_add_f32_e32 v70, v72, v70
	v_add_f32_e32 v70, v73, v70
	v_add_f32_e32 v72, v69, v70
	ds_bpermute_b32 v73, v117, v72
	global_store_dwordx4 v[92:93], v[64:67], off offset:576
	v_cvt_pk_bf16_f32 v70, v64, v65
	v_cvt_pk_bf16_f32 v69, v74, v75
	v_cvt_pk_bf16_f32 v71, v66, v67
	s_waitcnt lgkmcnt(0)
	v_add_f32_e32 v64, v72, v73
	ds_bpermute_b32 v65, v116, v64
	v_permlane16_swap_b32_e32 v68, v70
	v_permlane16_swap_b32_e32 v69, v71
	global_store_dwordx4 v[94:95], v[68:71], off offset:256
	s_and_saveexec_b64 s[30:31], vcc
	s_cbranch_execz .LBB0_862
	v_lshlrev_b64 v[66:67], 7, v[80:81]
	v_lshl_add_u64 v[66:67], s[28:29], 0, v[66:67]
	s_waitcnt lgkmcnt(0)
	v_add_f32_e32 v64, v64, v65
	global_store_dword v[66:67], v64, off
.LBB0_862:
	s_or_b64 exec, exec, s[30:31]
	v_add_u32_e32 v64, 0x80, v130
	s_waitcnt lgkmcnt(0)
	v_ashrrev_i32_e32 v65, 31, v64
	v_lshlrev_b64 v[66:67], 11, v[64:65]
	v_lshl_add_u64 v[70:71], v[66:67], 0, s[24:25]
	v_or_b32_e32 v66, v70, v132
	v_mov_b32_e32 v67, v71
	v_readlane_b32 s40, v254, 2
	v_lshlrev_b64 v[72:73], 2, v[66:67]
	v_readlane_b32 s41, v254, 3
	v_lshl_add_u64 v[76:77], s[92:93], 0, v[72:73]
	v_lshl_add_u64 v[78:79], v[70:71], 1, v[124:125]
	v_lshl_add_u64 v[74:75], s[40:41], 0, v[72:73]
	global_load_dwordx4 v[200:203], v[74:75], off
	global_load_dwordx4 v[204:207], v[74:75], off offset:64
	global_load_dwordx4 v[208:211], v[74:75], off offset:512
	global_load_dwordx4 v[212:215], v[74:75], off offset:576
	v_readlane_b32 s42, v254, 4
	v_readlane_b32 s43, v254, 5
	v_readlane_b32 s44, v254, 6
	v_readlane_b32 s45, v254, 7
	v_readlane_b32 s46, v254, 8
	v_readlane_b32 s47, v254, 9
	v_readlane_b32 s48, v254, 10
	v_readlane_b32 s49, v254, 11
	v_readlane_b32 s50, v254, 12
	v_readlane_b32 s51, v254, 13
	v_readlane_b32 s52, v254, 14
	v_readlane_b32 s53, v254, 15
	v_readlane_b32 s54, v254, 16
	v_readlane_b32 s55, v254, 17
	s_waitcnt vmcnt(3)
	v_pk_add_f32 v[60:61], v[60:61], v[200:201]
	v_pk_add_f32 v[62:63], v[62:63], v[202:203]
	global_store_dwordx4 v[76:77], v[60:63], off
	v_cvt_pk_bf16_f32 v70, v60, v61
	v_cvt_pk_bf16_f32 v71, v62, v63
	v_pk_mul_f32 v[60:61], v[60:61], v[60:61]
	v_pk_mul_f32 v[62:63], v[62:63], v[62:63]
	v_add_f32_e32 v60, v60, v61
	v_add_f32_e32 v60, v62, v60
	v_add_f32_e32 v60, v63, v60
	s_waitcnt vmcnt(3)
	v_pk_add_f32 v[56:57], v[56:57], v[204:205]
	v_pk_add_f32 v[58:59], v[58:59], v[206:207]
	v_cvt_pk_bf16_f32 v72, v56, v57
	v_cvt_pk_bf16_f32 v73, v58, v59
	s_nop 0
	v_permlane16_swap_b32_e32 v70, v72
	v_permlane16_swap_b32_e32 v71, v73
	global_store_dwordx4 v[76:77], v[56:59], off offset:64
	global_store_dwordx4 v[78:79], v[70:73], off
	s_nop 0
	v_pk_mul_f32 v[56:57], v[56:57], v[56:57]
	v_pk_mul_f32 v[58:59], v[58:59], v[58:59]
	v_add_f32_e32 v56, v56, v57
	v_add_f32_e32 v56, v58, v56
	v_add_f32_e32 v56, v59, v56
	v_add_f32_e32 v60, v60, v56
	s_waitcnt vmcnt(4)
	v_pk_add_f32 v[52:53], v[52:53], v[208:209]
	v_pk_add_f32 v[54:55], v[54:55], v[210:211]
	global_store_dwordx4 v[76:77], v[52:55], off offset:512
	v_pk_mul_f32 v[56:57], v[52:53], v[52:53]
	v_pk_mul_f32 v[58:59], v[54:55], v[54:55]
	v_cvt_pk_bf16_f32 v52, v52, v53
	v_add_f32_e32 v53, v56, v57
	v_add_f32_e32 v53, v58, v53
	v_add_f32_e32 v53, v59, v53
	v_add_f32_e32 v53, v60, v53
	s_waitcnt vmcnt(4)
	v_pk_add_f32 v[48:49], v[48:49], v[212:213]
	v_pk_add_f32 v[50:51], v[50:51], v[214:215]
	v_pk_mul_f32 v[56:57], v[48:49], v[48:49]
	v_pk_mul_f32 v[58:59], v[50:51], v[50:51]
	v_add_f32_e32 v56, v56, v57
	v_add_f32_e32 v56, v58, v56
	v_add_f32_e32 v56, v59, v56
	v_add_f32_e32 v56, v53, v56
	ds_bpermute_b32 v57, v117, v56
	v_cvt_pk_bf16_f32 v53, v54, v55
	global_store_dwordx4 v[76:77], v[48:51], off offset:576
	v_cvt_pk_bf16_f32 v54, v48, v49
	v_cvt_pk_bf16_f32 v55, v50, v51
	s_waitcnt lgkmcnt(0)
	v_add_f32_e32 v48, v56, v57
	ds_bpermute_b32 v49, v116, v48
	v_permlane16_swap_b32_e32 v52, v54
	v_permlane16_swap_b32_e32 v53, v55
	global_store_dwordx4 v[78:79], v[52:55], off offset:256
	s_and_saveexec_b64 s[30:31], vcc
	s_cbranch_execz .LBB0_864
; DEVINL float shx(float v, int m, int lane) { return __int_as_float(__builtin_amdgcn_ds_bpermute((lane ^ m) << 2, __float_as_int(v))); }
; DEVINL void phase_gemm_res(const Params& p, const u16* A, int lda, const u16* B, int K, const float* resid, char* smem, int wv) {
;     ...
; #pragma unroll
;     for (int ai = 0; ai < 2; ++ai)
; #pragma unroll
;       for (int m = 0; m < 4; ++m) {
;         int row = m0 + ai * 128 + wr * 64 + m * 16 + fr;
;         size_t off = (size_t)row * DM + n0 + wc * 32 + fq * 4;
;         size_t offw = (size_t)row * DM + n0 + wc * 32 + (fq & 1) * 16 + (fq >> 1) * 8;
;         float ss = 0.f;
; #pragma unroll
;         for (int bj = 0; bj < 2; ++bj) {
;           f32x4 vv[2];
; #pragma unroll
;           for (int n = 0; n < 2; ++n) {
;             float4 rv = *(const float4*)(resid + off + bj * 128 + n * 16);
;             f32x4 v = acc[ai][bj][m][n];
;             v[0] += rv.x; v[1] += rv.y; v[2] += rv.z; v[3] += rv.w;
;             float4 ov; ov.x = v[0]; ov.y = v[1]; ov.z = v[2]; ov.w = v[3];
;             *(float4*)(out + off + bj * 128 + n * 16) = ov;
;             ss += sumsq4(v);
;             vv[n] = v;
;           }
;           *(u32x4*)(xb + offw + bj * 128) = widen2(vv[0], vv[1]);
;         }
;         ss += shx(ss, 16, lane); ss += shx(ss, 32, lane);
;         if (fq == 0) part[(size_t)row * 32 + pn * 4 + wc] = ss;
;       }
	v_lshlrev_b64 v[50:51], 7, v[64:65]
	v_lshl_add_u64 v[50:51], s[28:29], 0, v[50:51]
	s_waitcnt lgkmcnt(0)
	v_add_f32_e32 v48, v48, v49
	global_store_dword v[50:51], v48, off
.LBB0_864:
	s_or_b64 exec, exec, s[30:31]
	v_add_u32_e32 v48, 0x90, v130
	s_waitcnt lgkmcnt(0)
	v_ashrrev_i32_e32 v49, 31, v48
	v_lshlrev_b64 v[50:51], 11, v[48:49]
	v_lshl_add_u64 v[54:55], v[50:51], 0, s[24:25]
	v_or_b32_e32 v50, v54, v132
	v_mov_b32_e32 v51, v55
	v_readlane_b32 s40, v254, 2
	v_lshlrev_b64 v[56:57], 2, v[50:51]
	v_readlane_b32 s41, v254, 3
	v_lshl_add_u64 v[60:61], s[92:93], 0, v[56:57]
	v_lshl_add_u64 v[62:63], v[54:55], 1, v[124:125]
	v_lshl_add_u64 v[58:59], s[40:41], 0, v[56:57]
	global_load_dwordx4 v[200:203], v[58:59], off
	global_load_dwordx4 v[204:207], v[58:59], off offset:64
	global_load_dwordx4 v[208:211], v[58:59], off offset:512
	global_load_dwordx4 v[212:215], v[58:59], off offset:576
	v_readlane_b32 s42, v254, 4
	v_readlane_b32 s43, v254, 5
	v_readlane_b32 s44, v254, 6
	v_readlane_b32 s45, v254, 7
	v_readlane_b32 s46, v254, 8
	v_readlane_b32 s47, v254, 9
	v_readlane_b32 s48, v254, 10
	v_readlane_b32 s49, v254, 11
	v_readlane_b32 s50, v254, 12
	v_readlane_b32 s51, v254, 13
	v_readlane_b32 s52, v254, 14
	v_readlane_b32 s53, v254, 15
	v_readlane_b32 s54, v254, 16
	v_readlane_b32 s55, v254, 17
	s_waitcnt vmcnt(3)
	v_pk_add_f32 v[44:45], v[44:45], v[200:201]
	v_pk_add_f32 v[46:47], v[46:47], v[202:203]
	global_store_dwordx4 v[60:61], v[44:47], off
	v_cvt_pk_bf16_f32 v54, v44, v45
	v_cvt_pk_bf16_f32 v55, v46, v47
	v_pk_mul_f32 v[44:45], v[44:45], v[44:45]
	v_pk_mul_f32 v[46:47], v[46:47], v[46:47]
	v_add_f32_e32 v44, v44, v45
	v_add_f32_e32 v44, v46, v44
	v_add_f32_e32 v44, v47, v44
	s_waitcnt vmcnt(3)
	v_pk_add_f32 v[40:41], v[40:41], v[204:205]
	v_pk_add_f32 v[42:43], v[42:43], v[206:207]
	v_cvt_pk_bf16_f32 v56, v40, v41
	v_cvt_pk_bf16_f32 v57, v42, v43
	s_nop 0
	v_permlane16_swap_b32_e32 v54, v56
	v_permlane16_swap_b32_e32 v55, v57
	global_store_dwordx4 v[60:61], v[40:43], off offset:64
	global_store_dwordx4 v[62:63], v[54:57], off
	s_nop 0
	v_pk_mul_f32 v[40:41], v[40:41], v[40:41]
	v_pk_mul_f32 v[42:43], v[42:43], v[42:43]
	v_add_f32_e32 v40, v40, v41
	v_add_f32_e32 v40, v42, v40
	v_add_f32_e32 v40, v43, v40
	v_add_f32_e32 v44, v44, v40
	s_waitcnt vmcnt(4)
	v_pk_add_f32 v[36:37], v[36:37], v[208:209]
	v_pk_add_f32 v[38:39], v[38:39], v[210:211]
	global_store_dwordx4 v[60:61], v[36:39], off offset:512
	v_pk_mul_f32 v[40:41], v[36:37], v[36:37]
	v_pk_mul_f32 v[42:43], v[38:39], v[38:39]
	v_cvt_pk_bf16_f32 v36, v36, v37
	v_add_f32_e32 v37, v40, v41
	v_add_f32_e32 v37, v42, v37
	v_add_f32_e32 v37, v43, v37
	v_add_f32_e32 v37, v44, v37
	s_waitcnt vmcnt(4)
	v_pk_add_f32 v[32:33], v[32:33], v[212:213]
	v_pk_add_f32 v[34:35], v[34:35], v[214:215]
	v_pk_mul_f32 v[40:41], v[32:33], v[32:33]
	v_pk_mul_f32 v[42:43], v[34:35], v[34:35]
	v_add_f32_e32 v40, v40, v41
	v_add_f32_e32 v40, v42, v40
	v_add_f32_e32 v40, v43, v40
	v_add_f32_e32 v40, v37, v40
	ds_bpermute_b32 v41, v117, v40
	v_cvt_pk_bf16_f32 v37, v38, v39
	global_store_dwordx4 v[60:61], v[32:35], off offset:576
	v_cvt_pk_bf16_f32 v38, v32, v33
	v_cvt_pk_bf16_f32 v39, v34, v35
	s_waitcnt lgkmcnt(0)
	v_add_f32_e32 v32, v40, v41
	ds_bpermute_b32 v33, v116, v32
	v_permlane16_swap_b32_e32 v36, v38
	v_permlane16_swap_b32_e32 v37, v39
	global_store_dwordx4 v[62:63], v[36:39], off offset:256
	s_and_saveexec_b64 s[30:31], vcc
	s_cbranch_execz .LBB0_866
	v_lshlrev_b64 v[34:35], 7, v[48:49]
	v_lshl_add_u64 v[34:35], s[28:29], 0, v[34:35]
	s_waitcnt lgkmcnt(0)
	v_add_f32_e32 v32, v32, v33
	global_store_dword v[34:35], v32, off
; DEVINL float shx(float v, int m, int lane) { return __int_as_float(__builtin_amdgcn_ds_bpermute((lane ^ m) << 2, __float_as_int(v))); }
; DEVINL void phase_gemm_res(const Params& p, const u16* A, int lda, const u16* B, int K, const float* resid, char* smem, int wv) {
;     ...
; #pragma unroll
;     for (int ai = 0; ai < 2; ++ai)
; #pragma unroll
;       for (int m = 0; m < 4; ++m) {
;         int row = m0 + ai * 128 + wr * 64 + m * 16 + fr;
;         size_t off = (size_t)row * DM + n0 + wc * 32 + fq * 4;
;         size_t offw = (size_t)row * DM + n0 + wc * 32 + (fq & 1) * 16 + (fq >> 1) * 8;
;         float ss = 0.f;
; #pragma unroll
;         for (int bj = 0; bj < 2; ++bj) {
;           f32x4 vv[2];
; #pragma unroll
;           for (int n = 0; n < 2; ++n) {
;             float4 rv = *(const float4*)(resid + off + bj * 128 + n * 16);
;             f32x4 v = acc[ai][bj][m][n];
;             v[0] += rv.x; v[1] += rv.y; v[2] += rv.z; v[3] += rv.w;
;             float4 ov; ov.x = v[0]; ov.y = v[1]; ov.z = v[2]; ov.w = v[3];
;             *(float4*)(out + off + bj * 128 + n * 16) = ov;
;             ss += sumsq4(v);
;             vv[n] = v;
;           }
;           *(u32x4*)(xb + offw + bj * 128) = widen2(vv[0], vv[1]);
;         }
;         ss += shx(ss, 16, lane); ss += shx(ss, 32, lane);
;         if (fq == 0) part[(size_t)row * 32 + pn * 4 + wc] = ss;
;       }
.LBB0_866:
	s_or_b64 exec, exec, s[30:31]
	v_add_u32_e32 v32, 0xa0, v130
	s_waitcnt lgkmcnt(0)
	v_ashrrev_i32_e32 v33, 31, v32
	v_lshlrev_b64 v[34:35], 11, v[32:33]
	v_lshl_add_u64 v[34:35], v[34:35], 0, s[24:25]
	v_or_b32_e32 v36, v34, v132
	v_mov_b32_e32 v37, v35
	v_readlane_b32 s40, v254, 2
	v_lshlrev_b64 v[36:37], 2, v[36:37]
	v_readlane_b32 s41, v254, 3
	v_lshl_add_u64 v[40:41], s[92:93], 0, v[36:37]
	v_lshl_add_u64 v[42:43], v[34:35], 1, v[124:125]
	v_lshl_add_u64 v[38:39], s[40:41], 0, v[36:37]
	global_load_dwordx4 v[200:203], v[38:39], off
	global_load_dwordx4 v[204:207], v[38:39], off offset:64
	global_load_dwordx4 v[208:211], v[38:39], off offset:512
	global_load_dwordx4 v[212:215], v[38:39], off offset:576
	v_readlane_b32 s42, v254, 4
	v_readlane_b32 s43, v254, 5
	v_readlane_b32 s44, v254, 6
	v_readlane_b32 s45, v254, 7
	v_readlane_b32 s46, v254, 8
	v_readlane_b32 s47, v254, 9
	v_readlane_b32 s48, v254, 10
	v_readlane_b32 s49, v254, 11
	v_readlane_b32 s50, v254, 12
	v_readlane_b32 s51, v254, 13
	v_readlane_b32 s52, v254, 14
	v_readlane_b32 s53, v254, 15
	v_readlane_b32 s54, v254, 16
	v_readlane_b32 s55, v254, 17
	s_waitcnt vmcnt(3)
	v_pk_add_f32 v[28:29], v[28:29], v[200:201]
	v_pk_add_f32 v[30:31], v[30:31], v[202:203]
	global_store_dwordx4 v[40:41], v[28:31], off
	v_pk_mul_f32 v[44:45], v[28:29], v[28:29]
	v_pk_mul_f32 v[46:47], v[30:31], v[30:31]
	v_cvt_pk_bf16_f32 v28, v28, v29
	v_cvt_pk_bf16_f32 v29, v30, v31
	s_waitcnt vmcnt(3)
	v_pk_add_f32 v[24:25], v[24:25], v[204:205]
	v_pk_add_f32 v[26:27], v[26:27], v[206:207]
	v_cvt_pk_bf16_f32 v30, v24, v25
	v_cvt_pk_bf16_f32 v31, v26, v27
	s_nop 0
	v_permlane16_swap_b32_e32 v28, v30
	v_permlane16_swap_b32_e32 v29, v31
	global_store_dwordx4 v[40:41], v[24:27], off offset:64
	global_store_dwordx4 v[42:43], v[28:31], off
	v_pk_mul_f32 v[34:35], v[24:25], v[24:25]
	v_pk_mul_f32 v[36:37], v[26:27], v[26:27]
	v_add_f32_e32 v34, v34, v35
	v_add_f32_e32 v34, v36, v34
	v_add_f32_e32 v34, v37, v34
	s_waitcnt vmcnt(4)
	v_pk_add_f32 v[20:21], v[20:21], v[208:209]
	v_pk_add_f32 v[22:23], v[22:23], v[210:211]
	global_store_dwordx4 v[40:41], v[20:23], off offset:512
	v_pk_mul_f32 v[28:29], v[20:21], v[20:21]
	v_add_f32_e32 v38, v44, v45
	v_pk_mul_f32 v[30:31], v[22:23], v[22:23]
	v_add_f32_e32 v38, v46, v38
	v_add_f32_e32 v28, v28, v29
	v_add_f32_e32 v38, v47, v38
	v_add_f32_e32 v28, v30, v28
	v_add_f32_e32 v34, v38, v34
	v_add_f32_e32 v28, v31, v28
	v_add_f32_e32 v28, v34, v28
	v_cvt_pk_bf16_f32 v20, v20, v21
	v_cvt_pk_bf16_f32 v21, v22, v23
	s_waitcnt vmcnt(4)
	v_pk_add_f32 v[16:17], v[16:17], v[212:213]
	v_pk_add_f32 v[18:19], v[18:19], v[214:215]
	v_pk_mul_f32 v[24:25], v[16:17], v[16:17]
	v_pk_mul_f32 v[26:27], v[18:19], v[18:19]
	v_add_f32_e32 v24, v24, v25
	v_add_f32_e32 v24, v26, v24
	v_add_f32_e32 v24, v27, v24
	v_add_f32_e32 v24, v28, v24
	global_store_dwordx4 v[40:41], v[16:19], off offset:576
	v_cvt_pk_bf16_f32 v22, v16, v17
	ds_bpermute_b32 v16, v117, v24
	v_cvt_pk_bf16_f32 v23, v18, v19
	v_permlane16_swap_b32_e32 v20, v22
	s_nop 0
	v_permlane16_swap_b32_e32 v21, v23
	s_waitcnt lgkmcnt(0)
	v_add_f32_e32 v16, v24, v16
	ds_bpermute_b32 v17, v116, v16
	global_store_dwordx4 v[42:43], v[20:23], off offset:256
	s_and_saveexec_b64 s[30:31], vcc
	s_cbranch_execz .LBB0_868
	v_lshlrev_b64 v[18:19], 7, v[32:33]
	v_lshl_add_u64 v[18:19], s[28:29], 0, v[18:19]
	s_waitcnt lgkmcnt(0)
	v_add_f32_e32 v16, v16, v17
	global_store_dword v[18:19], v16, off
.LBB0_868:
	s_or_b64 exec, exec, s[30:31]
	v_add_u32_e32 v16, 0xb0, v130
	s_waitcnt lgkmcnt(0)
	v_ashrrev_i32_e32 v17, 31, v16
	v_lshlrev_b64 v[18:19], 11, v[16:17]
	v_lshl_add_u64 v[18:19], v[18:19], 0, s[24:25]
	v_or_b32_e32 v20, v18, v132
	v_mov_b32_e32 v21, v19
	v_readlane_b32 s40, v254, 2
	v_lshlrev_b64 v[20:21], 2, v[20:21]
	v_readlane_b32 s41, v254, 3
	v_lshl_add_u64 v[24:25], s[92:93], 0, v[20:21]
	v_lshl_add_u64 v[26:27], v[18:19], 1, v[124:125]
	v_lshl_add_u64 v[22:23], s[40:41], 0, v[20:21]
	global_load_dwordx4 v[200:203], v[22:23], off
	global_load_dwordx4 v[204:207], v[22:23], off offset:64
	global_load_dwordx4 v[208:211], v[22:23], off offset:512
	global_load_dwordx4 v[212:215], v[22:23], off offset:576
	v_readlane_b32 s42, v254, 4
	v_readlane_b32 s43, v254, 5
	v_readlane_b32 s44, v254, 6
	v_readlane_b32 s45, v254, 7
	v_readlane_b32 s46, v254, 8
	v_readlane_b32 s47, v254, 9
	v_readlane_b32 s48, v254, 10
	v_readlane_b32 s49, v254, 11
	v_readlane_b32 s50, v254, 12
	v_readlane_b32 s51, v254, 13
	v_readlane_b32 s52, v254, 14
	v_readlane_b32 s53, v254, 15
	v_readlane_b32 s54, v254, 16
	v_readlane_b32 s55, v254, 17
	s_waitcnt vmcnt(3)
	v_pk_add_f32 v[12:13], v[12:13], v[200:201]
	v_pk_add_f32 v[14:15], v[14:15], v[202:203]
	global_store_dwordx4 v[24:25], v[12:15], off
	v_pk_mul_f32 v[28:29], v[12:13], v[12:13]
	v_pk_mul_f32 v[30:31], v[14:15], v[14:15]
	v_cvt_pk_bf16_f32 v12, v12, v13
	v_cvt_pk_bf16_f32 v13, v14, v15
	s_waitcnt vmcnt(3)
	v_pk_add_f32 v[8:9], v[8:9], v[204:205]
	v_pk_add_f32 v[10:11], v[10:11], v[206:207]
	v_cvt_pk_bf16_f32 v14, v8, v9
	v_cvt_pk_bf16_f32 v15, v10, v11
	s_nop 0
	v_permlane16_swap_b32_e32 v12, v14
	v_permlane16_swap_b32_e32 v13, v15
	global_store_dwordx4 v[24:25], v[8:11], off offset:64
	global_store_dwordx4 v[26:27], v[12:15], off
	v_pk_mul_f32 v[18:19], v[8:9], v[8:9]
	v_pk_mul_f32 v[20:21], v[10:11], v[10:11]
	v_add_f32_e32 v18, v18, v19
	v_add_f32_e32 v18, v20, v18
	v_add_f32_e32 v18, v21, v18
	s_waitcnt vmcnt(4)
	v_pk_add_f32 v[4:5], v[4:5], v[208:209]
	v_pk_add_f32 v[6:7], v[6:7], v[210:211]
	global_store_dwordx4 v[24:25], v[4:7], off offset:512
	v_pk_mul_f32 v[12:13], v[4:5], v[4:5]
	v_add_f32_e32 v22, v28, v29
	v_pk_mul_f32 v[14:15], v[6:7], v[6:7]
	v_add_f32_e32 v22, v30, v22
	v_add_f32_e32 v12, v12, v13
	v_add_f32_e32 v22, v31, v22
	v_add_f32_e32 v12, v14, v12
	v_add_f32_e32 v18, v22, v18
	v_add_f32_e32 v12, v15, v12
	v_add_f32_e32 v12, v18, v12
	v_cvt_pk_bf16_f32 v4, v4, v5
	v_cvt_pk_bf16_f32 v5, v6, v7
	s_waitcnt vmcnt(4)
	v_pk_add_f32 v[0:1], v[0:1], v[212:213]
	v_pk_add_f32 v[2:3], v[2:3], v[214:215]
	v_pk_mul_f32 v[8:9], v[0:1], v[0:1]
	v_pk_mul_f32 v[10:11], v[2:3], v[2:3]
	v_add_f32_e32 v8, v8, v9
	v_add_f32_e32 v8, v10, v8
	v_add_f32_e32 v8, v11, v8
	v_add_f32_e32 v8, v12, v8
	global_store_dwordx4 v[24:25], v[0:3], off offset:576
	v_cvt_pk_bf16_f32 v6, v0, v1
	ds_bpermute_b32 v0, v117, v8
	v_cvt_pk_bf16_f32 v7, v2, v3
	v_permlane16_swap_b32_e32 v4, v6
	s_nop 0
	v_permlane16_swap_b32_e32 v5, v7
	s_waitcnt lgkmcnt(0)
	v_add_f32_e32 v0, v8, v0
	ds_bpermute_b32 v1, v116, v0
	global_store_dwordx4 v[26:27], v[4:7], off offset:256
	s_and_saveexec_b64 s[24:25], vcc
	s_cbranch_execz .LBB0_845
	v_lshlrev_b64 v[2:3], 7, v[16:17]
	v_lshl_add_u64 v[2:3], s[28:29], 0, v[2:3]
	s_waitcnt lgkmcnt(0)
	v_add_f32_e32 v0, v0, v1
	global_store_dword v[2:3], v0, off
	s_branch .LBB0_845

; DEVINL float shx(float v, int m, int lane) { return __int_as_float(__builtin_amdgcn_ds_bpermute((lane ^ m) << 2, __float_as_int(v))); }
; DEVINL void phase_gemm_res(const Params& p, const u16* A, int lda, const u16* B, int K, const float* resid, char* smem, int wv) {
;     ...
; #pragma unroll
;     for (int ai = 0; ai < 2; ++ai)
; #pragma unroll
;       for (int m = 0; m < 4; ++m) {
;         int row = m0 + ai * 128 + wr * 64 + m * 16 + fr;
;         size_t off = (size_t)row * DM + n0 + wc * 32 + fq * 4;
;         size_t offw = (size_t)row * DM + n0 + wc * 32 + (fq & 1) * 16 + (fq >> 1) * 8;
;         float ss = 0.f;
; #pragma unroll
;         for (int bj = 0; bj < 2; ++bj) {
;           f32x4 vv[2];
; #pragma unroll
;           for (int n = 0; n < 2; ++n) {
;             float4 rv = *(const float4*)(resid + off + bj * 128 + n * 16);
;             f32x4 v = acc[ai][bj][m][n];
;             v[0] += rv.x; v[1] += rv.y; v[2] += rv.z; v[3] += rv.w;
;             float4 ov; ov.x = v[0]; ov.y = v[1]; ov.z = v[2]; ov.w = v[3];
;             *(float4*)(out + off + bj * 128 + n * 16) = ov;
;             ss += sumsq4(v);
;             vv[n] = v;
;           }
;           *(u32x4*)(xb + offw + bj * 128) = widen2(vv[0], vv[1]);
;         }
;         ss += shx(ss, 16, lane); ss += shx(ss, 32, lane);
;         if (fq == 0) part[(size_t)row * 32 + pn * 4 + wc] = ss;
;       }
.LBB0_970:
	s_ashr_i32 s0, s29, 2
	s_andn2_b32 s0, s0, 63
	v_or_b32_e32 v128, s0, v128
	s_bfe_u32 s27, s29, 0x20006
	v_add_u32_e32 v130, s26, v128
	v_lshrrev_b32_e32 v128, 2, v151
	v_and_b32_e32 v131, 16, v151
	s_lshl_b32 s0, s27, 5
	v_and_b32_e32 v136, 12, v128
	v_and_or_b32 v128, v128, 8, v131
	v_ashrrev_i32_e32 v131, 31, v130
	s_or_b32 s22, s22, s0
	v_lshlrev_b64 v[134:135], 11, v[130:131]
	v_lshlrev_b32_e32 v128, 1, v128
	v_lshl_add_u64 v[142:143], v[134:135], 0, s[22:23]
	v_lshl_add_u64 v[132:133], s[90:91], 0, v[128:129]
	v_lshl_add_u64 v[134:135], v[142:143], 2, s[92:93]
	v_lshlrev_b32_e32 v128, 2, v136
	v_lshl_add_u64 v[146:147], v[134:135], 0, v[128:129]
	global_load_dwordx4 v[200:203], v[146:147], off
	global_load_dwordx4 v[204:207], v[146:147], off offset:64
	global_load_dwordx4 v[208:211], v[146:147], off offset:512
	global_load_dwordx4 v[212:215], v[146:147], off offset:576
	v_lshl_add_u64 v[148:149], v[142:143], 1, v[132:133]
	s_lshl_b32 s0, s28, 2
	s_ashr_i32 s1, s0, 31
	s_lshl_b64 s[0:1], s[0:1], 2
	s_add_u32 s0, s60, s0
	s_addc_u32 s1, s61, s1
	s_lshl_b32 s26, s27, 2
	s_add_u32 s26, s0, s26
	s_addc_u32 s27, s1, 0
	s_waitcnt vmcnt(2)
	v_pk_add_f32 v[124:125], v[124:125], v[200:201]
	v_pk_add_f32 v[126:127], v[126:127], v[202:203]
	v_pk_add_f32 v[134:135], v[120:121], v[204:205]
	v_pk_add_f32 v[136:137], v[122:123], v[206:207]
	v_cvt_pk_bf16_f32 v120, v124, v125
	v_cvt_pk_bf16_f32 v121, v126, v127
	v_cvt_pk_bf16_f32 v122, v134, v135
	v_cvt_pk_bf16_f32 v123, v136, v137
	s_nop 0
	v_permlane16_swap_b32_e32 v120, v122
	v_permlane16_swap_b32_e32 v121, v123
	global_store_dwordx4 v[146:147], v[124:127], off
	global_store_dwordx4 v[146:147], v[134:137], off offset:64
	global_store_dwordx4 v[148:149], v[120:123], off
	s_nop 1
	v_and_b32_e32 v120, 63, v151
	v_lshlrev_b32_e32 v122, 2, v120
	v_cmp_gt_u32_e32 vcc, 16, v120
	v_xor_b32_e32 v121, 64, v122
	v_xor_b32_e32 v120, 0x80, v122
	v_pk_mul_f32 v[122:123], v[124:125], v[124:125]
	v_pk_mul_f32 v[124:125], v[126:127], v[126:127]
	v_pk_mul_f32 v[126:127], v[134:135], v[134:135]
	v_pk_mul_f32 v[134:135], v[136:137], v[136:137]
	v_add_f32_e32 v126, v126, v127
	v_add_f32_e32 v122, v122, v123
	v_add_f32_e32 v123, v134, v126
	v_add_f32_e32 v122, v124, v122
	v_add_f32_e32 v123, v135, v123
	v_add_f32_e32 v122, v125, v122
	v_add_f32_e32 v136, v122, v123
	s_waitcnt vmcnt(3)
	v_pk_add_f32 v[112:113], v[112:113], v[208:209]
	v_pk_add_f32 v[114:115], v[114:115], v[210:211]
	v_pk_add_f32 v[116:117], v[116:117], v[212:213]
	v_pk_mul_f32 v[122:123], v[112:113], v[112:113]
	v_pk_add_f32 v[118:119], v[118:119], v[214:215]
	v_pk_mul_f32 v[124:125], v[114:115], v[114:115]
	v_pk_mul_f32 v[126:127], v[116:117], v[116:117]
	v_add_f32_e32 v122, v122, v123
	v_pk_mul_f32 v[134:135], v[118:119], v[118:119]
	v_add_f32_e32 v123, v126, v127
	v_add_f32_e32 v122, v124, v122
	v_add_f32_e32 v123, v134, v123
	v_add_f32_e32 v122, v125, v122
	v_add_f32_e32 v123, v135, v123
	v_add_f32_e32 v122, v136, v122
	v_add_f32_e32 v126, v122, v123
	ds_bpermute_b32 v127, v121, v126
	global_store_dwordx4 v[146:147], v[112:115], off offset:512
	v_cvt_pk_bf16_f32 v122, v112, v113
	v_cvt_pk_bf16_f32 v123, v114, v115
	v_cvt_pk_bf16_f32 v124, v116, v117
	s_waitcnt lgkmcnt(0)
	v_add_f32_e32 v112, v126, v127
	ds_bpermute_b32 v113, v120, v112
	v_cvt_pk_bf16_f32 v125, v118, v119
	v_permlane16_swap_b32_e32 v122, v124
	s_nop 0
	v_permlane16_swap_b32_e32 v123, v125
	global_store_dwordx4 v[146:147], v[116:119], off offset:576
	global_store_dwordx4 v[148:149], v[122:125], off offset:256
	s_and_saveexec_b64 s[28:29], vcc
	s_cbranch_execz .LBB0_972
	v_lshlrev_b64 v[114:115], 7, v[130:131]
	v_lshl_add_u64 v[114:115], s[26:27], 0, v[114:115]
	s_waitcnt lgkmcnt(0)
	v_add_f32_e32 v112, v112, v113
	global_store_dword v[114:115], v112, off
.LBB0_972:
	s_or_b64 exec, exec, s[28:29]
	v_or_b32_e32 v112, 16, v130
	s_waitcnt lgkmcnt(0)
	v_ashrrev_i32_e32 v113, 31, v112
	v_lshlrev_b64 v[114:115], 11, v[112:113]
	v_lshl_add_u64 v[118:119], v[114:115], 0, s[22:23]
	v_lshl_add_u64 v[114:115], v[118:119], 2, s[92:93]
	v_lshl_add_u64 v[126:127], v[114:115], 0, v[128:129]
	global_load_dwordx4 v[200:203], v[126:127], off
	global_load_dwordx4 v[204:207], v[126:127], off offset:64
	global_load_dwordx4 v[208:211], v[126:127], off offset:512
	global_load_dwordx4 v[212:215], v[126:127], off offset:576
	v_lshl_add_u64 v[118:119], v[118:119], 1, v[132:133]
	s_waitcnt vmcnt(3)
	v_pk_add_f32 v[108:109], v[108:109], v[200:201]
	v_pk_add_f32 v[110:111], v[110:111], v[202:203]
	s_waitcnt vmcnt(2)
	v_pk_add_f32 v[104:105], v[104:105], v[204:205]
	v_pk_add_f32 v[106:107], v[106:107], v[206:207]
	v_cvt_pk_bf16_f32 v114, v108, v109
	v_cvt_pk_bf16_f32 v115, v110, v111
	v_cvt_pk_bf16_f32 v116, v104, v105
	v_cvt_pk_bf16_f32 v117, v106, v107
	s_nop 0
	v_permlane16_swap_b32_e32 v114, v116
	v_permlane16_swap_b32_e32 v115, v117
	global_store_dwordx4 v[126:127], v[108:111], off
	global_store_dwordx4 v[126:127], v[104:107], off offset:64
	global_store_dwordx4 v[118:119], v[114:117], off
	s_nop 0
	v_pk_mul_f32 v[108:109], v[108:109], v[108:109]
	v_pk_mul_f32 v[104:105], v[104:105], v[104:105]
	v_pk_mul_f32 v[110:111], v[110:111], v[110:111]
	v_pk_mul_f32 v[106:107], v[106:107], v[106:107]
	v_add_f32_e32 v104, v104, v105
	v_add_f32_e32 v105, v108, v109
	v_add_f32_e32 v104, v106, v104
	v_add_f32_e32 v105, v110, v105
	v_add_f32_e32 v104, v107, v104
	v_add_f32_e32 v105, v111, v105
	v_add_f32_e32 v131, v105, v104
	s_waitcnt vmcnt(4)
	v_pk_add_f32 v[96:97], v[96:97], v[208:209]
	v_pk_add_f32 v[98:99], v[98:99], v[210:211]
	s_waitcnt vmcnt(3)
	v_pk_add_f32 v[100:101], v[100:101], v[212:213]
	v_pk_mul_f32 v[104:105], v[96:97], v[96:97]
	v_pk_add_f32 v[102:103], v[102:103], v[214:215]
	v_pk_mul_f32 v[106:107], v[98:99], v[98:99]
	v_pk_mul_f32 v[108:109], v[100:101], v[100:101]
	v_add_f32_e32 v104, v104, v105
	v_pk_mul_f32 v[110:111], v[102:103], v[102:103]
	v_add_f32_e32 v105, v108, v109
	v_add_f32_e32 v104, v106, v104
	v_add_f32_e32 v105, v110, v105
	v_add_f32_e32 v104, v107, v104
	v_add_f32_e32 v105, v111, v105
	v_add_f32_e32 v104, v131, v104
	v_add_f32_e32 v108, v104, v105
	ds_bpermute_b32 v109, v121, v108
	global_store_dwordx4 v[126:127], v[96:99], off offset:512
	v_cvt_pk_bf16_f32 v104, v96, v97
	v_cvt_pk_bf16_f32 v105, v98, v99
	v_cvt_pk_bf16_f32 v106, v100, v101
	s_waitcnt lgkmcnt(0)
	v_add_f32_e32 v96, v108, v109
	ds_bpermute_b32 v97, v120, v96
	v_cvt_pk_bf16_f32 v107, v102, v103
	v_permlane16_swap_b32_e32 v104, v106
	s_nop 0
	v_permlane16_swap_b32_e32 v105, v107
	global_store_dwordx4 v[126:127], v[100:103], off offset:576
	global_store_dwordx4 v[118:119], v[104:107], off offset:256
	s_and_saveexec_b64 s[28:29], vcc
	s_cbranch_execz .LBB0_974
	v_lshlrev_b64 v[98:99], 7, v[112:113]
	v_lshl_add_u64 v[98:99], s[26:27], 0, v[98:99]
	s_waitcnt lgkmcnt(0)
	v_add_f32_e32 v96, v96, v97
	global_store_dword v[98:99], v96, off
; DEVINL float shx(float v, int m, int lane) { return __int_as_float(__builtin_amdgcn_ds_bpermute((lane ^ m) << 2, __float_as_int(v))); }
; DEVINL void phase_gemm_res(const Params& p, const u16* A, int lda, const u16* B, int K, const float* resid, char* smem, int wv) {
;     ...
; #pragma unroll
;     for (int ai = 0; ai < 2; ++ai)
; #pragma unroll
;       for (int m = 0; m < 4; ++m) {
;         int row = m0 + ai * 128 + wr * 64 + m * 16 + fr;
;         size_t off = (size_t)row * DM + n0 + wc * 32 + fq * 4;
;         size_t offw = (size_t)row * DM + n0 + wc * 32 + (fq & 1) * 16 + (fq >> 1) * 8;
;         float ss = 0.f;
; #pragma unroll
;         for (int bj = 0; bj < 2; ++bj) {
;           f32x4 vv[2];
; #pragma unroll
;           for (int n = 0; n < 2; ++n) {
;             float4 rv = *(const float4*)(resid + off + bj * 128 + n * 16);
;             f32x4 v = acc[ai][bj][m][n];
;             v[0] += rv.x; v[1] += rv.y; v[2] += rv.z; v[3] += rv.w;
;             float4 ov; ov.x = v[0]; ov.y = v[1]; ov.z = v[2]; ov.w = v[3];
;             *(float4*)(out + off + bj * 128 + n * 16) = ov;
;             ss += sumsq4(v);
;             vv[n] = v;
;           }
;           *(u32x4*)(xb + offw + bj * 128) = widen2(vv[0], vv[1]);
;         }
;         ss += shx(ss, 16, lane); ss += shx(ss, 32, lane);
;         if (fq == 0) part[(size_t)row * 32 + pn * 4 + wc] = ss;
;       }
.LBB0_974:
	s_or_b64 exec, exec, s[28:29]
	v_or_b32_e32 v96, 32, v130
	s_waitcnt lgkmcnt(0)
	v_ashrrev_i32_e32 v97, 31, v96
	v_lshlrev_b64 v[98:99], 11, v[96:97]
	v_lshl_add_u64 v[106:107], v[98:99], 0, s[22:23]
	v_lshl_add_u64 v[98:99], v[106:107], 2, s[92:93]
	v_lshl_add_u64 v[108:109], v[98:99], 0, v[128:129]
	global_load_dwordx4 v[200:203], v[108:109], off
	global_load_dwordx4 v[204:207], v[108:109], off offset:64
	global_load_dwordx4 v[208:211], v[108:109], off offset:512
	global_load_dwordx4 v[212:215], v[108:109], off offset:576
	v_lshl_add_u64 v[106:107], v[106:107], 1, v[132:133]
	s_waitcnt vmcnt(3)
	v_pk_add_f32 v[92:93], v[92:93], v[200:201]
	v_pk_add_f32 v[94:95], v[94:95], v[202:203]
	s_waitcnt vmcnt(2)
	v_pk_add_f32 v[88:89], v[88:89], v[204:205]
	v_pk_add_f32 v[90:91], v[90:91], v[206:207]
	v_cvt_pk_bf16_f32 v98, v92, v93
	v_cvt_pk_bf16_f32 v99, v94, v95
	v_cvt_pk_bf16_f32 v100, v88, v89
	v_cvt_pk_bf16_f32 v101, v90, v91
	s_nop 0
	v_permlane16_swap_b32_e32 v98, v100
	v_permlane16_swap_b32_e32 v99, v101
	global_store_dwordx4 v[108:109], v[92:95], off
	global_store_dwordx4 v[108:109], v[88:91], off offset:64
	global_store_dwordx4 v[106:107], v[98:101], off
	s_nop 0
	v_pk_mul_f32 v[92:93], v[92:93], v[92:93]
	v_pk_mul_f32 v[88:89], v[88:89], v[88:89]
	v_pk_mul_f32 v[94:95], v[94:95], v[94:95]
	v_pk_mul_f32 v[90:91], v[90:91], v[90:91]
	v_add_f32_e32 v88, v88, v89
	v_add_f32_e32 v89, v92, v93
	v_add_f32_e32 v88, v90, v88
	v_add_f32_e32 v89, v94, v89
	v_add_f32_e32 v88, v91, v88
	v_add_f32_e32 v89, v95, v89
	v_add_f32_e32 v110, v89, v88
	s_waitcnt vmcnt(4)
	v_pk_add_f32 v[80:81], v[80:81], v[208:209]
	v_pk_add_f32 v[82:83], v[82:83], v[210:211]
	s_waitcnt vmcnt(3)
	v_pk_add_f32 v[84:85], v[84:85], v[212:213]
	v_pk_mul_f32 v[88:89], v[80:81], v[80:81]
	v_pk_add_f32 v[86:87], v[86:87], v[214:215]
	v_pk_mul_f32 v[90:91], v[82:83], v[82:83]
	v_pk_mul_f32 v[92:93], v[84:85], v[84:85]
	v_add_f32_e32 v88, v88, v89
	v_pk_mul_f32 v[94:95], v[86:87], v[86:87]
	v_add_f32_e32 v89, v92, v93
	v_add_f32_e32 v88, v90, v88
	v_add_f32_e32 v89, v94, v89
	v_add_f32_e32 v88, v91, v88
	v_add_f32_e32 v89, v95, v89
	v_add_f32_e32 v88, v110, v88
	v_add_f32_e32 v92, v88, v89
	ds_bpermute_b32 v93, v121, v92
	global_store_dwordx4 v[108:109], v[80:83], off offset:512
	v_cvt_pk_bf16_f32 v88, v80, v81
	v_cvt_pk_bf16_f32 v89, v82, v83
	v_cvt_pk_bf16_f32 v90, v84, v85
	s_waitcnt lgkmcnt(0)
	v_add_f32_e32 v80, v92, v93
	ds_bpermute_b32 v81, v120, v80
	v_cvt_pk_bf16_f32 v91, v86, v87
	v_permlane16_swap_b32_e32 v88, v90
	s_nop 0
	v_permlane16_swap_b32_e32 v89, v91
	global_store_dwordx4 v[108:109], v[84:87], off offset:576
	global_store_dwordx4 v[106:107], v[88:91], off offset:256
	s_and_saveexec_b64 s[28:29], vcc
	s_cbranch_execz .LBB0_976
	v_lshlrev_b64 v[82:83], 7, v[96:97]
	v_lshl_add_u64 v[82:83], s[26:27], 0, v[82:83]
	s_waitcnt lgkmcnt(0)
	v_add_f32_e32 v80, v80, v81
	global_store_dword v[82:83], v80, off
.LBB0_976:
	s_or_b64 exec, exec, s[28:29]
	v_or_b32_e32 v80, 48, v130
	s_waitcnt lgkmcnt(0)
	v_ashrrev_i32_e32 v81, 31, v80
	v_lshlrev_b64 v[82:83], 11, v[80:81]
	v_lshl_add_u64 v[90:91], v[82:83], 0, s[22:23]
	v_lshl_add_u64 v[82:83], v[90:91], 2, s[92:93]
	v_lshl_add_u64 v[92:93], v[82:83], 0, v[128:129]
	global_load_dwordx4 v[200:203], v[92:93], off
	global_load_dwordx4 v[204:207], v[92:93], off offset:64
	global_load_dwordx4 v[208:211], v[92:93], off offset:512
	global_load_dwordx4 v[212:215], v[92:93], off offset:576
	v_lshl_add_u64 v[90:91], v[90:91], 1, v[132:133]
	s_waitcnt vmcnt(3)
	v_pk_add_f32 v[76:77], v[76:77], v[200:201]
	v_pk_add_f32 v[78:79], v[78:79], v[202:203]
	s_waitcnt vmcnt(2)
	v_pk_add_f32 v[72:73], v[72:73], v[204:205]
	v_pk_add_f32 v[74:75], v[74:75], v[206:207]
	v_cvt_pk_bf16_f32 v82, v76, v77
	v_cvt_pk_bf16_f32 v83, v78, v79
	v_cvt_pk_bf16_f32 v84, v72, v73
	v_cvt_pk_bf16_f32 v85, v74, v75
	s_nop 0
	v_permlane16_swap_b32_e32 v82, v84
	v_permlane16_swap_b32_e32 v83, v85
	global_store_dwordx4 v[92:93], v[76:79], off
	global_store_dwordx4 v[92:93], v[72:75], off offset:64
	global_store_dwordx4 v[90:91], v[82:85], off
	s_nop 0
	v_pk_mul_f32 v[76:77], v[76:77], v[76:77]
	v_pk_mul_f32 v[72:73], v[72:73], v[72:73]
	v_pk_mul_f32 v[78:79], v[78:79], v[78:79]
	v_pk_mul_f32 v[74:75], v[74:75], v[74:75]
	v_add_f32_e32 v72, v72, v73
	v_add_f32_e32 v73, v76, v77
	v_add_f32_e32 v72, v74, v72
	v_add_f32_e32 v73, v78, v73
	v_add_f32_e32 v72, v75, v72
	v_add_f32_e32 v73, v79, v73
	v_add_f32_e32 v94, v73, v72
	s_waitcnt vmcnt(4)
	v_pk_add_f32 v[64:65], v[64:65], v[208:209]
	v_pk_add_f32 v[66:67], v[66:67], v[210:211]
	s_waitcnt vmcnt(3)
	v_pk_add_f32 v[68:69], v[68:69], v[212:213]
	v_pk_mul_f32 v[72:73], v[64:65], v[64:65]
	v_pk_add_f32 v[70:71], v[70:71], v[214:215]
	v_pk_mul_f32 v[74:75], v[66:67], v[66:67]
	v_pk_mul_f32 v[76:77], v[68:69], v[68:69]
	v_add_f32_e32 v72, v72, v73
	v_pk_mul_f32 v[78:79], v[70:71], v[70:71]
	v_add_f32_e32 v73, v76, v77
	v_add_f32_e32 v72, v74, v72
	v_add_f32_e32 v73, v78, v73
	v_add_f32_e32 v72, v75, v72
	v_add_f32_e32 v73, v79, v73
	v_add_f32_e32 v72, v94, v72
	v_add_f32_e32 v76, v72, v73
	ds_bpermute_b32 v77, v121, v76
	global_store_dwordx4 v[92:93], v[64:67], off offset:512
	v_cvt_pk_bf16_f32 v72, v64, v65
	v_cvt_pk_bf16_f32 v73, v66, v67
	v_cvt_pk_bf16_f32 v74, v68, v69
	s_waitcnt lgkmcnt(0)
	v_add_f32_e32 v64, v76, v77
	ds_bpermute_b32 v65, v120, v64
	v_cvt_pk_bf16_f32 v75, v70, v71
	v_permlane16_swap_b32_e32 v72, v74
	s_nop 0
	v_permlane16_swap_b32_e32 v73, v75
	global_store_dwordx4 v[92:93], v[68:71], off offset:576
	global_store_dwordx4 v[90:91], v[72:75], off offset:256
	s_and_saveexec_b64 s[28:29], vcc
	s_cbranch_execz .LBB0_978
	v_lshlrev_b64 v[66:67], 7, v[80:81]
	v_lshl_add_u64 v[66:67], s[26:27], 0, v[66:67]
	s_waitcnt lgkmcnt(0)
	v_add_f32_e32 v64, v64, v65
	global_store_dword v[66:67], v64, off
; DEVINL float shx(float v, int m, int lane) { return __int_as_float(__builtin_amdgcn_ds_bpermute((lane ^ m) << 2, __float_as_int(v))); }
; DEVINL void phase_gemm_res(const Params& p, const u16* A, int lda, const u16* B, int K, const float* resid, char* smem, int wv) {
;     ...
; #pragma unroll
;     for (int ai = 0; ai < 2; ++ai)
; #pragma unroll
;       for (int m = 0; m < 4; ++m) {
;         int row = m0 + ai * 128 + wr * 64 + m * 16 + fr;
;         size_t off = (size_t)row * DM + n0 + wc * 32 + fq * 4;
;         size_t offw = (size_t)row * DM + n0 + wc * 32 + (fq & 1) * 16 + (fq >> 1) * 8;
;         float ss = 0.f;
; #pragma unroll
;         for (int bj = 0; bj < 2; ++bj) {
;           f32x4 vv[2];
; #pragma unroll
;           for (int n = 0; n < 2; ++n) {
;             float4 rv = *(const float4*)(resid + off + bj * 128 + n * 16);
;             f32x4 v = acc[ai][bj][m][n];
;             v[0] += rv.x; v[1] += rv.y; v[2] += rv.z; v[3] += rv.w;
;             float4 ov; ov.x = v[0]; ov.y = v[1]; ov.z = v[2]; ov.w = v[3];
;             *(float4*)(out + off + bj * 128 + n * 16) = ov;
;             ss += sumsq4(v);
;             vv[n] = v;
;           }
;           *(u32x4*)(xb + offw + bj * 128) = widen2(vv[0], vv[1]);
;         }
;         ss += shx(ss, 16, lane); ss += shx(ss, 32, lane);
;         if (fq == 0) part[(size_t)row * 32 + pn * 4 + wc] = ss;
;       }
.LBB0_978:
	s_or_b64 exec, exec, s[28:29]
	v_add_u32_e32 v64, 0x80, v130
	s_waitcnt lgkmcnt(0)
	v_ashrrev_i32_e32 v65, 31, v64
	v_lshlrev_b64 v[66:67], 11, v[64:65]
	v_lshl_add_u64 v[74:75], v[66:67], 0, s[22:23]
	v_lshl_add_u64 v[66:67], v[74:75], 2, s[92:93]
	v_lshl_add_u64 v[76:77], v[66:67], 0, v[128:129]
	global_load_dwordx4 v[200:203], v[76:77], off
	global_load_dwordx4 v[204:207], v[76:77], off offset:64
	global_load_dwordx4 v[208:211], v[76:77], off offset:512
	global_load_dwordx4 v[212:215], v[76:77], off offset:576
	v_lshl_add_u64 v[74:75], v[74:75], 1, v[132:133]
	s_waitcnt vmcnt(3)
	v_pk_add_f32 v[60:61], v[60:61], v[200:201]
	v_pk_add_f32 v[62:63], v[62:63], v[202:203]
	s_waitcnt vmcnt(2)
	v_pk_add_f32 v[56:57], v[56:57], v[204:205]
	v_pk_add_f32 v[58:59], v[58:59], v[206:207]
	v_cvt_pk_bf16_f32 v66, v60, v61
	v_cvt_pk_bf16_f32 v67, v62, v63
	v_cvt_pk_bf16_f32 v68, v56, v57
	v_cvt_pk_bf16_f32 v69, v58, v59
	s_nop 0
	v_permlane16_swap_b32_e32 v66, v68
	v_permlane16_swap_b32_e32 v67, v69
	global_store_dwordx4 v[76:77], v[60:63], off
	global_store_dwordx4 v[76:77], v[56:59], off offset:64
	global_store_dwordx4 v[74:75], v[66:69], off
	s_nop 0
	v_pk_mul_f32 v[60:61], v[60:61], v[60:61]
	v_pk_mul_f32 v[56:57], v[56:57], v[56:57]
	v_pk_mul_f32 v[62:63], v[62:63], v[62:63]
	v_pk_mul_f32 v[58:59], v[58:59], v[58:59]
	v_add_f32_e32 v56, v56, v57
	v_add_f32_e32 v57, v60, v61
	v_add_f32_e32 v56, v58, v56
	v_add_f32_e32 v57, v62, v57
	v_add_f32_e32 v56, v59, v56
	v_add_f32_e32 v57, v63, v57
	v_add_f32_e32 v78, v57, v56
	s_waitcnt vmcnt(4)
	v_pk_add_f32 v[48:49], v[48:49], v[208:209]
	v_pk_add_f32 v[50:51], v[50:51], v[210:211]
	s_waitcnt vmcnt(3)
	v_pk_add_f32 v[52:53], v[52:53], v[212:213]
	v_pk_mul_f32 v[56:57], v[48:49], v[48:49]
	v_pk_add_f32 v[54:55], v[54:55], v[214:215]
	v_pk_mul_f32 v[58:59], v[50:51], v[50:51]
	v_pk_mul_f32 v[60:61], v[52:53], v[52:53]
	v_add_f32_e32 v56, v56, v57
	v_pk_mul_f32 v[62:63], v[54:55], v[54:55]
	v_add_f32_e32 v57, v60, v61
	v_add_f32_e32 v56, v58, v56
	v_add_f32_e32 v57, v62, v57
	v_add_f32_e32 v56, v59, v56
	v_add_f32_e32 v57, v63, v57
	v_add_f32_e32 v56, v78, v56
	v_add_f32_e32 v60, v56, v57
	ds_bpermute_b32 v61, v121, v60
	global_store_dwordx4 v[76:77], v[48:51], off offset:512
	v_cvt_pk_bf16_f32 v56, v48, v49
	v_cvt_pk_bf16_f32 v57, v50, v51
	v_cvt_pk_bf16_f32 v58, v52, v53
	s_waitcnt lgkmcnt(0)
	v_add_f32_e32 v48, v60, v61
	ds_bpermute_b32 v49, v120, v48
	v_cvt_pk_bf16_f32 v59, v54, v55
	v_permlane16_swap_b32_e32 v56, v58
	s_nop 0
	v_permlane16_swap_b32_e32 v57, v59
	global_store_dwordx4 v[76:77], v[52:55], off offset:576
	global_store_dwordx4 v[74:75], v[56:59], off offset:256
	s_and_saveexec_b64 s[28:29], vcc
	s_cbranch_execz .LBB0_980
	v_lshlrev_b64 v[50:51], 7, v[64:65]
	v_lshl_add_u64 v[50:51], s[26:27], 0, v[50:51]
	s_waitcnt lgkmcnt(0)
	v_add_f32_e32 v48, v48, v49
	global_store_dword v[50:51], v48, off
.LBB0_980:
	s_or_b64 exec, exec, s[28:29]
	v_add_u32_e32 v48, 0x90, v130
	s_waitcnt lgkmcnt(0)
	v_ashrrev_i32_e32 v49, 31, v48
	v_lshlrev_b64 v[50:51], 11, v[48:49]
	v_lshl_add_u64 v[58:59], v[50:51], 0, s[22:23]
	v_lshl_add_u64 v[50:51], v[58:59], 2, s[92:93]
	v_lshl_add_u64 v[60:61], v[50:51], 0, v[128:129]
	global_load_dwordx4 v[200:203], v[60:61], off
	global_load_dwordx4 v[204:207], v[60:61], off offset:64
	global_load_dwordx4 v[208:211], v[60:61], off offset:512
	global_load_dwordx4 v[212:215], v[60:61], off offset:576
	v_lshl_add_u64 v[58:59], v[58:59], 1, v[132:133]
	s_waitcnt vmcnt(3)
	v_pk_add_f32 v[44:45], v[44:45], v[200:201]
	v_pk_add_f32 v[46:47], v[46:47], v[202:203]
	s_waitcnt vmcnt(2)
	v_pk_add_f32 v[40:41], v[40:41], v[204:205]
	v_pk_add_f32 v[42:43], v[42:43], v[206:207]
	v_cvt_pk_bf16_f32 v50, v44, v45
	v_cvt_pk_bf16_f32 v51, v46, v47
	v_cvt_pk_bf16_f32 v52, v40, v41
	v_cvt_pk_bf16_f32 v53, v42, v43
	s_nop 0
	v_permlane16_swap_b32_e32 v50, v52
	v_permlane16_swap_b32_e32 v51, v53
	global_store_dwordx4 v[60:61], v[44:47], off
	global_store_dwordx4 v[60:61], v[40:43], off offset:64
	global_store_dwordx4 v[58:59], v[50:53], off
	s_nop 0
	v_pk_mul_f32 v[44:45], v[44:45], v[44:45]
	v_pk_mul_f32 v[40:41], v[40:41], v[40:41]
	v_pk_mul_f32 v[46:47], v[46:47], v[46:47]
	v_pk_mul_f32 v[42:43], v[42:43], v[42:43]
	v_add_f32_e32 v40, v40, v41
	v_add_f32_e32 v41, v44, v45
	v_add_f32_e32 v40, v42, v40
	v_add_f32_e32 v41, v46, v41
	v_add_f32_e32 v40, v43, v40
	v_add_f32_e32 v41, v47, v41
	v_add_f32_e32 v62, v41, v40
	s_waitcnt vmcnt(4)
	v_pk_add_f32 v[32:33], v[32:33], v[208:209]
	v_pk_add_f32 v[34:35], v[34:35], v[210:211]
	s_waitcnt vmcnt(3)
	v_pk_add_f32 v[36:37], v[36:37], v[212:213]
	v_pk_mul_f32 v[40:41], v[32:33], v[32:33]
	v_pk_add_f32 v[38:39], v[38:39], v[214:215]
	v_pk_mul_f32 v[42:43], v[34:35], v[34:35]
	v_pk_mul_f32 v[44:45], v[36:37], v[36:37]
	v_add_f32_e32 v40, v40, v41
	v_pk_mul_f32 v[46:47], v[38:39], v[38:39]
	v_add_f32_e32 v41, v44, v45
	v_add_f32_e32 v40, v42, v40
	v_add_f32_e32 v41, v46, v41
	v_add_f32_e32 v40, v43, v40
	v_add_f32_e32 v41, v47, v41
	v_add_f32_e32 v40, v62, v40
	v_add_f32_e32 v44, v40, v41
	ds_bpermute_b32 v45, v121, v44
	global_store_dwordx4 v[60:61], v[32:35], off offset:512
	v_cvt_pk_bf16_f32 v40, v32, v33
	v_cvt_pk_bf16_f32 v41, v34, v35
	v_cvt_pk_bf16_f32 v42, v36, v37
	s_waitcnt lgkmcnt(0)
	v_add_f32_e32 v32, v44, v45
	ds_bpermute_b32 v33, v120, v32
	v_cvt_pk_bf16_f32 v43, v38, v39
	v_permlane16_swap_b32_e32 v40, v42
	s_nop 0
	v_permlane16_swap_b32_e32 v41, v43
	global_store_dwordx4 v[60:61], v[36:39], off offset:576
	global_store_dwordx4 v[58:59], v[40:43], off offset:256
	s_and_saveexec_b64 s[28:29], vcc
	s_cbranch_execz .LBB0_982
	v_lshlrev_b64 v[34:35], 7, v[48:49]
	v_lshl_add_u64 v[34:35], s[26:27], 0, v[34:35]
	s_waitcnt lgkmcnt(0)
	v_add_f32_e32 v32, v32, v33
	global_store_dword v[34:35], v32, off
; DEVINL float shx(float v, int m, int lane) { return __int_as_float(__builtin_amdgcn_ds_bpermute((lane ^ m) << 2, __float_as_int(v))); }
; DEVINL void phase_gemm_res(const Params& p, const u16* A, int lda, const u16* B, int K, const float* resid, char* smem, int wv) {
;     ...
; #pragma unroll
;     for (int ai = 0; ai < 2; ++ai)
; #pragma unroll
;       for (int m = 0; m < 4; ++m) {
;         int row = m0 + ai * 128 + wr * 64 + m * 16 + fr;
;         size_t off = (size_t)row * DM + n0 + wc * 32 + fq * 4;
;         size_t offw = (size_t)row * DM + n0 + wc * 32 + (fq & 1) * 16 + (fq >> 1) * 8;
;         float ss = 0.f;
; #pragma unroll
;         for (int bj = 0; bj < 2; ++bj) {
;           f32x4 vv[2];
; #pragma unroll
;           for (int n = 0; n < 2; ++n) {
;             float4 rv = *(const float4*)(resid + off + bj * 128 + n * 16);
;             f32x4 v = acc[ai][bj][m][n];
;             v[0] += rv.x; v[1] += rv.y; v[2] += rv.z; v[3] += rv.w;
;             float4 ov; ov.x = v[0]; ov.y = v[1]; ov.z = v[2]; ov.w = v[3];
;             *(float4*)(out + off + bj * 128 + n * 16) = ov;
;             ss += sumsq4(v);
;             vv[n] = v;
;           }
;           *(u32x4*)(xb + offw + bj * 128) = widen2(vv[0], vv[1]);
;         }
;         ss += shx(ss, 16, lane); ss += shx(ss, 32, lane);
;         if (fq == 0) part[(size_t)row * 32 + pn * 4 + wc] = ss;
;       }
.LBB0_982:
	s_or_b64 exec, exec, s[28:29]
	v_add_u32_e32 v32, 0xa0, v130
	s_waitcnt lgkmcnt(0)
	v_ashrrev_i32_e32 v33, 31, v32
	v_lshlrev_b64 v[34:35], 11, v[32:33]
	v_lshl_add_u64 v[42:43], v[34:35], 0, s[22:23]
	v_lshl_add_u64 v[34:35], v[42:43], 2, s[92:93]
	v_lshl_add_u64 v[44:45], v[34:35], 0, v[128:129]
	global_load_dwordx4 v[200:203], v[44:45], off
	global_load_dwordx4 v[204:207], v[44:45], off offset:64
	global_load_dwordx4 v[208:211], v[44:45], off offset:512
	global_load_dwordx4 v[212:215], v[44:45], off offset:576
	v_lshl_add_u64 v[42:43], v[42:43], 1, v[132:133]
	s_waitcnt vmcnt(3)
	v_pk_add_f32 v[28:29], v[28:29], v[200:201]
	v_pk_add_f32 v[30:31], v[30:31], v[202:203]
	s_waitcnt vmcnt(2)
	v_pk_add_f32 v[24:25], v[24:25], v[204:205]
	v_pk_add_f32 v[26:27], v[26:27], v[206:207]
	v_cvt_pk_bf16_f32 v34, v28, v29
	v_cvt_pk_bf16_f32 v35, v30, v31
	v_cvt_pk_bf16_f32 v36, v24, v25
	v_cvt_pk_bf16_f32 v37, v26, v27
	s_nop 0
	v_permlane16_swap_b32_e32 v34, v36
	v_permlane16_swap_b32_e32 v35, v37
	global_store_dwordx4 v[44:45], v[28:31], off
	global_store_dwordx4 v[44:45], v[24:27], off offset:64
	global_store_dwordx4 v[42:43], v[34:37], off
	s_nop 0
	v_pk_mul_f32 v[28:29], v[28:29], v[28:29]
	v_pk_mul_f32 v[24:25], v[24:25], v[24:25]
	v_pk_mul_f32 v[30:31], v[30:31], v[30:31]
	v_pk_mul_f32 v[26:27], v[26:27], v[26:27]
	v_add_f32_e32 v24, v24, v25
	v_add_f32_e32 v25, v28, v29
	v_add_f32_e32 v24, v26, v24
	v_add_f32_e32 v25, v30, v25
	v_add_f32_e32 v24, v27, v24
	v_add_f32_e32 v25, v31, v25
	v_add_f32_e32 v46, v25, v24
	s_waitcnt vmcnt(4)
	v_pk_add_f32 v[16:17], v[16:17], v[208:209]
	v_pk_add_f32 v[18:19], v[18:19], v[210:211]
	s_waitcnt vmcnt(3)
	v_pk_add_f32 v[20:21], v[20:21], v[212:213]
	v_pk_mul_f32 v[24:25], v[16:17], v[16:17]
	v_pk_add_f32 v[22:23], v[22:23], v[214:215]
	v_pk_mul_f32 v[26:27], v[18:19], v[18:19]
	v_pk_mul_f32 v[28:29], v[20:21], v[20:21]
	v_add_f32_e32 v24, v24, v25
	v_pk_mul_f32 v[30:31], v[22:23], v[22:23]
	v_add_f32_e32 v25, v28, v29
	v_add_f32_e32 v24, v26, v24
	v_add_f32_e32 v25, v30, v25
	v_add_f32_e32 v24, v27, v24
	v_add_f32_e32 v25, v31, v25
	v_add_f32_e32 v24, v46, v24
	v_add_f32_e32 v28, v24, v25
	ds_bpermute_b32 v29, v121, v28
	global_store_dwordx4 v[44:45], v[16:19], off offset:512
	v_cvt_pk_bf16_f32 v24, v16, v17
	v_cvt_pk_bf16_f32 v25, v18, v19
	v_cvt_pk_bf16_f32 v26, v20, v21
	s_waitcnt lgkmcnt(0)
	v_add_f32_e32 v16, v28, v29
	ds_bpermute_b32 v17, v120, v16
	v_cvt_pk_bf16_f32 v27, v22, v23
	v_permlane16_swap_b32_e32 v24, v26
	s_nop 0
	v_permlane16_swap_b32_e32 v25, v27
	global_store_dwordx4 v[44:45], v[20:23], off offset:576
	global_store_dwordx4 v[42:43], v[24:27], off offset:256
	s_and_saveexec_b64 s[28:29], vcc
	s_cbranch_execz .LBB0_984
	v_lshlrev_b64 v[18:19], 7, v[32:33]
	v_lshl_add_u64 v[18:19], s[26:27], 0, v[18:19]
	s_waitcnt lgkmcnt(0)
	v_add_f32_e32 v16, v16, v17
	global_store_dword v[18:19], v16, off
.LBB0_984:
	s_or_b64 exec, exec, s[28:29]
	v_add_u32_e32 v16, 0xb0, v130
	s_waitcnt lgkmcnt(0)
	v_ashrrev_i32_e32 v17, 31, v16
	v_lshlrev_b64 v[18:19], 11, v[16:17]
	v_lshl_add_u64 v[18:19], v[18:19], 0, s[22:23]
	v_lshl_add_u64 v[20:21], v[18:19], 2, s[92:93]
	v_lshl_add_u64 v[24:25], v[20:21], 0, v[128:129]
	global_load_dwordx4 v[200:203], v[24:25], off
	global_load_dwordx4 v[204:207], v[24:25], off offset:64
	global_load_dwordx4 v[208:211], v[24:25], off offset:512
	global_load_dwordx4 v[212:215], v[24:25], off offset:576
	v_lshl_add_u64 v[18:19], v[18:19], 1, v[132:133]
	s_waitcnt vmcnt(3)
	v_pk_add_f32 v[12:13], v[12:13], v[200:201]
	v_pk_add_f32 v[14:15], v[14:15], v[202:203]
	v_pk_mul_f32 v[26:27], v[12:13], v[12:13]
	global_store_dwordx4 v[24:25], v[12:15], off
	v_pk_mul_f32 v[28:29], v[14:15], v[14:15]
	s_waitcnt vmcnt(3)
	v_pk_add_f32 v[8:9], v[8:9], v[204:205]
	v_pk_add_f32 v[10:11], v[10:11], v[206:207]
	v_cvt_pk_bf16_f32 v12, v12, v13
	v_cvt_pk_bf16_f32 v13, v14, v15
	v_cvt_pk_bf16_f32 v14, v8, v9
	v_cvt_pk_bf16_f32 v15, v10, v11
	s_nop 0
	v_permlane16_swap_b32_e32 v12, v14
	v_permlane16_swap_b32_e32 v13, v15
	global_store_dwordx4 v[24:25], v[8:11], off offset:64
	global_store_dwordx4 v[18:19], v[12:15], off
	v_pk_mul_f32 v[20:21], v[8:9], v[8:9]
	v_pk_mul_f32 v[22:23], v[10:11], v[10:11]
	v_add_f32_e32 v20, v20, v21
	v_add_f32_e32 v21, v26, v27
	v_add_f32_e32 v20, v22, v20
	v_add_f32_e32 v21, v28, v21
	v_add_f32_e32 v20, v23, v20
	v_add_f32_e32 v21, v29, v21
	v_add_f32_e32 v20, v21, v20
	s_waitcnt vmcnt(4)
	v_pk_add_f32 v[4:5], v[4:5], v[208:209]
	v_pk_add_f32 v[6:7], v[6:7], v[210:211]
	v_pk_mul_f32 v[12:13], v[4:5], v[4:5]
	v_pk_mul_f32 v[14:15], v[6:7], v[6:7]
	v_add_f32_e32 v12, v12, v13
	v_add_f32_e32 v12, v14, v12
	v_add_f32_e32 v12, v15, v12
	v_add_f32_e32 v12, v20, v12
	global_store_dwordx4 v[24:25], v[4:7], off offset:512
	s_waitcnt vmcnt(4)
	v_pk_add_f32 v[0:1], v[0:1], v[212:213]
	v_pk_add_f32 v[2:3], v[2:3], v[214:215]
	v_pk_mul_f32 v[8:9], v[0:1], v[0:1]
	v_pk_mul_f32 v[10:11], v[2:3], v[2:3]
	v_add_f32_e32 v8, v8, v9
	v_add_f32_e32 v8, v10, v8
	v_add_f32_e32 v8, v11, v8
	v_add_f32_e32 v8, v12, v8
	global_store_dwordx4 v[24:25], v[0:3], off offset:576
	v_cvt_pk_bf16_f32 v4, v4, v5
	v_cvt_pk_bf16_f32 v5, v6, v7
	v_cvt_pk_bf16_f32 v6, v0, v1
	ds_bpermute_b32 v0, v121, v8
	v_cvt_pk_bf16_f32 v7, v2, v3
	v_permlane16_swap_b32_e32 v4, v6
	s_nop 0
	v_permlane16_swap_b32_e32 v5, v7
	s_waitcnt lgkmcnt(0)
	v_add_f32_e32 v0, v8, v0
	ds_bpermute_b32 v1, v120, v0
	global_store_dwordx4 v[18:19], v[4:7], off offset:256
	s_and_saveexec_b64 s[22:23], vcc
	s_cbranch_execz .LBB0_961
	v_lshlrev_b64 v[2:3], 7, v[16:17]
	v_lshl_add_u64 v[2:3], s[26:27], 0, v[2:3]
	s_waitcnt lgkmcnt(0)
	v_add_f32_e32 v0, v0, v1
	global_store_dword v[2:3], v0, off
	s_branch .LBB0_961

; DEVINL float shx(float v, int m, int lane) { return __int_as_float(__builtin_amdgcn_ds_bpermute((lane ^ m) << 2, __float_as_int(v))); }
; DEVINL void phase_gemm_res(const Params& p, const u16* A, int lda, const u16* B, int K, const float* resid, char* smem, int wv) {
;     ...
; #pragma unroll
;     for (int ai = 0; ai < 2; ++ai)
; #pragma unroll
;       for (int m = 0; m < 4; ++m) {
;         int row = m0 + ai * 128 + wr * 64 + m * 16 + fr;
;         size_t off = (size_t)row * DM + n0 + wc * 32 + fq * 4;
;         size_t offw = (size_t)row * DM + n0 + wc * 32 + (fq & 1) * 16 + (fq >> 1) * 8;
;         float ss = 0.f;
; #pragma unroll
;         for (int bj = 0; bj < 2; ++bj) {
;           f32x4 vv[2];
; #pragma unroll
;           for (int n = 0; n < 2; ++n) {
;             float4 rv = *(const float4*)(resid + off + bj * 128 + n * 16);
;             f32x4 v = acc[ai][bj][m][n];
;             v[0] += rv.x; v[1] += rv.y; v[2] += rv.z; v[3] += rv.w;
;             float4 ov; ov.x = v[0]; ov.y = v[1]; ov.z = v[2]; ov.w = v[3];
;             *(float4*)(out + off + bj * 128 + n * 16) = ov;
;             ss += sumsq4(v);
;             vv[n] = v;
;           }
;           *(u32x4*)(xb + offw + bj * 128) = widen2(vv[0], vv[1]);
;         }
;         ss += shx(ss, 16, lane); ss += shx(ss, 32, lane);
;         if (fq == 0) part[(size_t)row * 32 + pn * 4 + wc] = ss;
;       }
.LBB0_1876:
	s_ashr_i32 s25, s29, 2
	s_andn2_b32 s25, s25, 63
	v_or_b32_e32 v128, s25, v128
	s_bfe_u32 s37, s29, 0x20006
	v_add_u32_e32 v132, s24, v128
	s_lshl_b32 s24, s37, 5
	v_lshrrev_b32_e32 v128, 2, v151
	v_and_b32_e32 v130, 16, v151
	v_ashrrev_i32_e32 v133, 31, v132
	s_or_b32 s22, s22, s24
	v_and_b32_e32 v136, 12, v128
	v_and_or_b32 v128, v128, 8, v130
	v_lshlrev_b64 v[134:135], 11, v[132:133]
	v_lshlrev_b32_e32 v128, 1, v128
	v_lshl_add_u64 v[142:143], v[134:135], 0, s[22:23]
	v_lshl_add_u64 v[130:131], s[90:91], 0, v[128:129]
	v_lshl_add_u64 v[134:135], v[142:143], 2, s[92:93]
	v_lshlrev_b32_e32 v128, 2, v136
	v_lshl_add_u64 v[146:147], v[134:135], 0, v[128:129]
	global_load_dwordx4 v[200:203], v[146:147], off
	global_load_dwordx4 v[204:207], v[146:147], off offset:64
	global_load_dwordx4 v[208:211], v[146:147], off offset:512
	global_load_dwordx4 v[212:215], v[146:147], off offset:576
	v_lshl_add_u64 v[148:149], v[142:143], 1, v[130:131]
	s_lshl_b32 s24, s28, 2
	s_ashr_i32 s25, s24, 31
	s_lshl_b64 s[24:25], s[24:25], 2
	s_add_u32 s24, s60, s24
	s_addc_u32 s25, s61, s25
	s_lshl_b32 s28, s37, 2
	s_add_u32 s24, s24, s28
	s_addc_u32 s25, s25, 0
	s_waitcnt vmcnt(2)
	v_pk_add_f32 v[124:125], v[124:125], v[200:201]
	v_pk_add_f32 v[126:127], v[126:127], v[202:203]
	v_pk_add_f32 v[134:135], v[120:121], v[204:205]
	v_pk_add_f32 v[136:137], v[122:123], v[206:207]
	v_cvt_pk_bf16_f32 v120, v124, v125
	v_cvt_pk_bf16_f32 v121, v126, v127
	v_cvt_pk_bf16_f32 v122, v134, v135
	v_cvt_pk_bf16_f32 v123, v136, v137
	s_nop 0
	v_permlane16_swap_b32_e32 v120, v122
	v_permlane16_swap_b32_e32 v121, v123
	global_store_dwordx4 v[146:147], v[124:127], off
	global_store_dwordx4 v[146:147], v[134:137], off offset:64
	global_store_dwordx4 v[148:149], v[120:123], off
	s_nop 1
	v_and_b32_e32 v120, 63, v151
	v_lshlrev_b32_e32 v122, 2, v120
	v_cmp_gt_u32_e32 vcc, 16, v120
	v_xor_b32_e32 v121, 64, v122
	v_xor_b32_e32 v120, 0x80, v122
	v_pk_mul_f32 v[122:123], v[124:125], v[124:125]
	v_pk_mul_f32 v[124:125], v[126:127], v[126:127]
	v_pk_mul_f32 v[126:127], v[134:135], v[134:135]
	v_pk_mul_f32 v[134:135], v[136:137], v[136:137]
	v_add_f32_e32 v126, v126, v127
	v_add_f32_e32 v122, v122, v123
	v_add_f32_e32 v123, v134, v126
	v_add_f32_e32 v122, v124, v122
	v_add_f32_e32 v123, v135, v123
	v_add_f32_e32 v122, v125, v122
	v_add_f32_e32 v136, v122, v123
	s_waitcnt vmcnt(3)
	v_pk_add_f32 v[112:113], v[112:113], v[208:209]
	v_pk_add_f32 v[114:115], v[114:115], v[210:211]
	v_pk_add_f32 v[116:117], v[116:117], v[212:213]
	v_pk_mul_f32 v[122:123], v[112:113], v[112:113]
	v_pk_add_f32 v[118:119], v[118:119], v[214:215]
	v_pk_mul_f32 v[124:125], v[114:115], v[114:115]
	v_pk_mul_f32 v[126:127], v[116:117], v[116:117]
	v_add_f32_e32 v122, v122, v123
	v_pk_mul_f32 v[134:135], v[118:119], v[118:119]
	v_add_f32_e32 v123, v126, v127
	v_add_f32_e32 v122, v124, v122
	v_add_f32_e32 v123, v134, v123
	v_add_f32_e32 v122, v125, v122
	v_add_f32_e32 v123, v135, v123
	v_add_f32_e32 v122, v136, v122
	v_add_f32_e32 v126, v122, v123
	ds_bpermute_b32 v127, v121, v126
	global_store_dwordx4 v[146:147], v[112:115], off offset:512
	v_cvt_pk_bf16_f32 v122, v112, v113
	v_cvt_pk_bf16_f32 v123, v114, v115
	v_cvt_pk_bf16_f32 v124, v116, v117
	s_waitcnt lgkmcnt(0)
	v_add_f32_e32 v112, v126, v127
	ds_bpermute_b32 v113, v120, v112
	v_cvt_pk_bf16_f32 v125, v118, v119
	v_permlane16_swap_b32_e32 v122, v124
	s_nop 0
	v_permlane16_swap_b32_e32 v123, v125
	global_store_dwordx4 v[146:147], v[116:119], off offset:576
	global_store_dwordx4 v[148:149], v[122:125], off offset:256
	s_and_saveexec_b64 s[28:29], vcc
	s_cbranch_execz .LBB0_1878
	v_lshlrev_b64 v[114:115], 7, v[132:133]
	v_lshl_add_u64 v[114:115], s[24:25], 0, v[114:115]
	s_waitcnt lgkmcnt(0)
	v_add_f32_e32 v112, v112, v113
	global_store_dword v[114:115], v112, off
.LBB0_1878:
	s_or_b64 exec, exec, s[28:29]
	v_or_b32_e32 v112, 16, v132
	s_waitcnt lgkmcnt(0)
	v_ashrrev_i32_e32 v113, 31, v112
	v_lshlrev_b64 v[114:115], 11, v[112:113]
	v_lshl_add_u64 v[118:119], v[114:115], 0, s[22:23]
	v_lshl_add_u64 v[114:115], v[118:119], 2, s[92:93]
	v_lshl_add_u64 v[126:127], v[114:115], 0, v[128:129]
	global_load_dwordx4 v[200:203], v[126:127], off
	global_load_dwordx4 v[204:207], v[126:127], off offset:64
	global_load_dwordx4 v[208:211], v[126:127], off offset:512
	global_load_dwordx4 v[212:215], v[126:127], off offset:576
	v_lshl_add_u64 v[118:119], v[118:119], 1, v[130:131]
	s_waitcnt vmcnt(3)
	v_pk_add_f32 v[108:109], v[108:109], v[200:201]
	v_pk_add_f32 v[110:111], v[110:111], v[202:203]
	s_waitcnt vmcnt(2)
	v_pk_add_f32 v[104:105], v[104:105], v[204:205]
	v_pk_add_f32 v[106:107], v[106:107], v[206:207]
	v_cvt_pk_bf16_f32 v114, v108, v109
	v_cvt_pk_bf16_f32 v115, v110, v111
	v_cvt_pk_bf16_f32 v116, v104, v105
	v_cvt_pk_bf16_f32 v117, v106, v107
	s_nop 0
	v_permlane16_swap_b32_e32 v114, v116
	v_permlane16_swap_b32_e32 v115, v117
	global_store_dwordx4 v[126:127], v[108:111], off
	global_store_dwordx4 v[126:127], v[104:107], off offset:64
	global_store_dwordx4 v[118:119], v[114:117], off
	s_nop 0
	v_pk_mul_f32 v[108:109], v[108:109], v[108:109]
	v_pk_mul_f32 v[104:105], v[104:105], v[104:105]
	v_pk_mul_f32 v[110:111], v[110:111], v[110:111]
	v_pk_mul_f32 v[106:107], v[106:107], v[106:107]
	v_add_f32_e32 v104, v104, v105
	v_add_f32_e32 v105, v108, v109
	v_add_f32_e32 v104, v106, v104
	v_add_f32_e32 v105, v110, v105
	v_add_f32_e32 v104, v107, v104
	v_add_f32_e32 v105, v111, v105
	v_add_f32_e32 v133, v105, v104
	s_waitcnt vmcnt(4)
	v_pk_add_f32 v[96:97], v[96:97], v[208:209]
	v_pk_add_f32 v[98:99], v[98:99], v[210:211]
	s_waitcnt vmcnt(3)
	v_pk_add_f32 v[100:101], v[100:101], v[212:213]
	v_pk_mul_f32 v[104:105], v[96:97], v[96:97]
	v_pk_add_f32 v[102:103], v[102:103], v[214:215]
	v_pk_mul_f32 v[106:107], v[98:99], v[98:99]
	v_pk_mul_f32 v[108:109], v[100:101], v[100:101]
	v_add_f32_e32 v104, v104, v105
	v_pk_mul_f32 v[110:111], v[102:103], v[102:103]
	v_add_f32_e32 v105, v108, v109
	v_add_f32_e32 v104, v106, v104
	v_add_f32_e32 v105, v110, v105
	v_add_f32_e32 v104, v107, v104
	v_add_f32_e32 v105, v111, v105
	v_add_f32_e32 v104, v133, v104
	v_add_f32_e32 v108, v104, v105
	ds_bpermute_b32 v109, v121, v108
	global_store_dwordx4 v[126:127], v[96:99], off offset:512
	v_cvt_pk_bf16_f32 v104, v96, v97
	v_cvt_pk_bf16_f32 v105, v98, v99
	v_cvt_pk_bf16_f32 v106, v100, v101
	s_waitcnt lgkmcnt(0)
	v_add_f32_e32 v96, v108, v109
	ds_bpermute_b32 v97, v120, v96
	v_cvt_pk_bf16_f32 v107, v102, v103
	v_permlane16_swap_b32_e32 v104, v106
	s_nop 0
	v_permlane16_swap_b32_e32 v105, v107
	global_store_dwordx4 v[126:127], v[100:103], off offset:576
	global_store_dwordx4 v[118:119], v[104:107], off offset:256
	s_and_saveexec_b64 s[28:29], vcc
	s_cbranch_execz .LBB0_1880
	v_lshlrev_b64 v[98:99], 7, v[112:113]
	v_lshl_add_u64 v[98:99], s[24:25], 0, v[98:99]
	s_waitcnt lgkmcnt(0)
	v_add_f32_e32 v96, v96, v97
	global_store_dword v[98:99], v96, off
; DEVINL float shx(float v, int m, int lane) { return __int_as_float(__builtin_amdgcn_ds_bpermute((lane ^ m) << 2, __float_as_int(v))); }
; DEVINL void phase_gemm_res(const Params& p, const u16* A, int lda, const u16* B, int K, const float* resid, char* smem, int wv) {
;     ...
; #pragma unroll
;     for (int ai = 0; ai < 2; ++ai)
; #pragma unroll
;       for (int m = 0; m < 4; ++m) {
;         int row = m0 + ai * 128 + wr * 64 + m * 16 + fr;
;         size_t off = (size_t)row * DM + n0 + wc * 32 + fq * 4;
;         size_t offw = (size_t)row * DM + n0 + wc * 32 + (fq & 1) * 16 + (fq >> 1) * 8;
;         float ss = 0.f;
; #pragma unroll
;         for (int bj = 0; bj < 2; ++bj) {
;           f32x4 vv[2];
; #pragma unroll
;           for (int n = 0; n < 2; ++n) {
;             float4 rv = *(const float4*)(resid + off + bj * 128 + n * 16);
;             f32x4 v = acc[ai][bj][m][n];
;             v[0] += rv.x; v[1] += rv.y; v[2] += rv.z; v[3] += rv.w;
;             float4 ov; ov.x = v[0]; ov.y = v[1]; ov.z = v[2]; ov.w = v[3];
;             *(float4*)(out + off + bj * 128 + n * 16) = ov;
;             ss += sumsq4(v);
;             vv[n] = v;
;           }
;           *(u32x4*)(xb + offw + bj * 128) = widen2(vv[0], vv[1]);
;         }
;         ss += shx(ss, 16, lane); ss += shx(ss, 32, lane);
;         if (fq == 0) part[(size_t)row * 32 + pn * 4 + wc] = ss;
;       }
.LBB0_1880:
	s_or_b64 exec, exec, s[28:29]
	v_or_b32_e32 v96, 32, v132
	s_waitcnt lgkmcnt(0)
	v_ashrrev_i32_e32 v97, 31, v96
	v_lshlrev_b64 v[98:99], 11, v[96:97]
	v_lshl_add_u64 v[106:107], v[98:99], 0, s[22:23]
	v_lshl_add_u64 v[98:99], v[106:107], 2, s[92:93]
	v_lshl_add_u64 v[108:109], v[98:99], 0, v[128:129]
	global_load_dwordx4 v[200:203], v[108:109], off
	global_load_dwordx4 v[204:207], v[108:109], off offset:64
	global_load_dwordx4 v[208:211], v[108:109], off offset:512
	global_load_dwordx4 v[212:215], v[108:109], off offset:576
	v_lshl_add_u64 v[106:107], v[106:107], 1, v[130:131]
	s_waitcnt vmcnt(3)
	v_pk_add_f32 v[92:93], v[92:93], v[200:201]
	v_pk_add_f32 v[94:95], v[94:95], v[202:203]
	s_waitcnt vmcnt(2)
	v_pk_add_f32 v[88:89], v[88:89], v[204:205]
	v_pk_add_f32 v[90:91], v[90:91], v[206:207]
	v_cvt_pk_bf16_f32 v98, v92, v93
	v_cvt_pk_bf16_f32 v99, v94, v95
	v_cvt_pk_bf16_f32 v100, v88, v89
	v_cvt_pk_bf16_f32 v101, v90, v91
	s_nop 0
	v_permlane16_swap_b32_e32 v98, v100
	v_permlane16_swap_b32_e32 v99, v101
	global_store_dwordx4 v[108:109], v[92:95], off
	global_store_dwordx4 v[108:109], v[88:91], off offset:64
	global_store_dwordx4 v[106:107], v[98:101], off
	s_nop 0
	v_pk_mul_f32 v[92:93], v[92:93], v[92:93]
	v_pk_mul_f32 v[88:89], v[88:89], v[88:89]
	v_pk_mul_f32 v[94:95], v[94:95], v[94:95]
	v_pk_mul_f32 v[90:91], v[90:91], v[90:91]
	v_add_f32_e32 v88, v88, v89
	v_add_f32_e32 v89, v92, v93
	v_add_f32_e32 v88, v90, v88
	v_add_f32_e32 v89, v94, v89
	v_add_f32_e32 v88, v91, v88
	v_add_f32_e32 v89, v95, v89
	v_add_f32_e32 v110, v89, v88
	s_waitcnt vmcnt(4)
	v_pk_add_f32 v[80:81], v[80:81], v[208:209]
	v_pk_add_f32 v[82:83], v[82:83], v[210:211]
	s_waitcnt vmcnt(3)
	v_pk_add_f32 v[84:85], v[84:85], v[212:213]
	v_pk_mul_f32 v[88:89], v[80:81], v[80:81]
	v_pk_add_f32 v[86:87], v[86:87], v[214:215]
	v_pk_mul_f32 v[90:91], v[82:83], v[82:83]
	v_pk_mul_f32 v[92:93], v[84:85], v[84:85]
	v_add_f32_e32 v88, v88, v89
	v_pk_mul_f32 v[94:95], v[86:87], v[86:87]
	v_add_f32_e32 v89, v92, v93
	v_add_f32_e32 v88, v90, v88
	v_add_f32_e32 v89, v94, v89
	v_add_f32_e32 v88, v91, v88
	v_add_f32_e32 v89, v95, v89
	v_add_f32_e32 v88, v110, v88
	v_add_f32_e32 v92, v88, v89
	ds_bpermute_b32 v93, v121, v92
	global_store_dwordx4 v[108:109], v[80:83], off offset:512
	v_cvt_pk_bf16_f32 v88, v80, v81
	v_cvt_pk_bf16_f32 v89, v82, v83
	v_cvt_pk_bf16_f32 v90, v84, v85
	s_waitcnt lgkmcnt(0)
	v_add_f32_e32 v80, v92, v93
	ds_bpermute_b32 v81, v120, v80
	v_cvt_pk_bf16_f32 v91, v86, v87
	v_permlane16_swap_b32_e32 v88, v90
	s_nop 0
	v_permlane16_swap_b32_e32 v89, v91
	global_store_dwordx4 v[108:109], v[84:87], off offset:576
	global_store_dwordx4 v[106:107], v[88:91], off offset:256
	s_and_saveexec_b64 s[28:29], vcc
	s_cbranch_execz .LBB0_1882
	v_lshlrev_b64 v[82:83], 7, v[96:97]
	v_lshl_add_u64 v[82:83], s[24:25], 0, v[82:83]
	s_waitcnt lgkmcnt(0)
	v_add_f32_e32 v80, v80, v81
	global_store_dword v[82:83], v80, off
.LBB0_1882:
	s_or_b64 exec, exec, s[28:29]
	v_or_b32_e32 v80, 48, v132
	s_waitcnt lgkmcnt(0)
	v_ashrrev_i32_e32 v81, 31, v80
	v_lshlrev_b64 v[82:83], 11, v[80:81]
	v_lshl_add_u64 v[90:91], v[82:83], 0, s[22:23]
	v_lshl_add_u64 v[82:83], v[90:91], 2, s[92:93]
	v_lshl_add_u64 v[92:93], v[82:83], 0, v[128:129]
	global_load_dwordx4 v[200:203], v[92:93], off
	global_load_dwordx4 v[204:207], v[92:93], off offset:64
	global_load_dwordx4 v[208:211], v[92:93], off offset:512
	global_load_dwordx4 v[212:215], v[92:93], off offset:576
	v_lshl_add_u64 v[90:91], v[90:91], 1, v[130:131]
	s_waitcnt vmcnt(3)
	v_pk_add_f32 v[76:77], v[76:77], v[200:201]
	v_pk_add_f32 v[78:79], v[78:79], v[202:203]
	s_waitcnt vmcnt(2)
	v_pk_add_f32 v[72:73], v[72:73], v[204:205]
	v_pk_add_f32 v[74:75], v[74:75], v[206:207]
	v_cvt_pk_bf16_f32 v82, v76, v77
	v_cvt_pk_bf16_f32 v83, v78, v79
	v_cvt_pk_bf16_f32 v84, v72, v73
	v_cvt_pk_bf16_f32 v85, v74, v75
	s_nop 0
	v_permlane16_swap_b32_e32 v82, v84
	v_permlane16_swap_b32_e32 v83, v85
	global_store_dwordx4 v[92:93], v[76:79], off
	global_store_dwordx4 v[92:93], v[72:75], off offset:64
	global_store_dwordx4 v[90:91], v[82:85], off
	s_nop 0
	v_pk_mul_f32 v[76:77], v[76:77], v[76:77]
	v_pk_mul_f32 v[72:73], v[72:73], v[72:73]
	v_pk_mul_f32 v[78:79], v[78:79], v[78:79]
	v_pk_mul_f32 v[74:75], v[74:75], v[74:75]
	v_add_f32_e32 v72, v72, v73
	v_add_f32_e32 v73, v76, v77
	v_add_f32_e32 v72, v74, v72
	v_add_f32_e32 v73, v78, v73
	v_add_f32_e32 v72, v75, v72
	v_add_f32_e32 v73, v79, v73
	v_add_f32_e32 v94, v73, v72
	s_waitcnt vmcnt(4)
	v_pk_add_f32 v[64:65], v[64:65], v[208:209]
	v_pk_add_f32 v[66:67], v[66:67], v[210:211]
	s_waitcnt vmcnt(3)
	v_pk_add_f32 v[68:69], v[68:69], v[212:213]
	v_pk_mul_f32 v[72:73], v[64:65], v[64:65]
	v_pk_add_f32 v[70:71], v[70:71], v[214:215]
	v_pk_mul_f32 v[74:75], v[66:67], v[66:67]
	v_pk_mul_f32 v[76:77], v[68:69], v[68:69]
	v_add_f32_e32 v72, v72, v73
	v_pk_mul_f32 v[78:79], v[70:71], v[70:71]
	v_add_f32_e32 v73, v76, v77
	v_add_f32_e32 v72, v74, v72
	v_add_f32_e32 v73, v78, v73
	v_add_f32_e32 v72, v75, v72
	v_add_f32_e32 v73, v79, v73
	v_add_f32_e32 v72, v94, v72
	v_add_f32_e32 v76, v72, v73
	ds_bpermute_b32 v77, v121, v76
	global_store_dwordx4 v[92:93], v[64:67], off offset:512
	v_cvt_pk_bf16_f32 v72, v64, v65
	v_cvt_pk_bf16_f32 v73, v66, v67
	v_cvt_pk_bf16_f32 v74, v68, v69
	s_waitcnt lgkmcnt(0)
	v_add_f32_e32 v64, v76, v77
	ds_bpermute_b32 v65, v120, v64
	v_cvt_pk_bf16_f32 v75, v70, v71
	v_permlane16_swap_b32_e32 v72, v74
	s_nop 0
	v_permlane16_swap_b32_e32 v73, v75
	global_store_dwordx4 v[92:93], v[68:71], off offset:576
	global_store_dwordx4 v[90:91], v[72:75], off offset:256
	s_and_saveexec_b64 s[28:29], vcc
	s_cbranch_execz .LBB0_1884
	v_lshlrev_b64 v[66:67], 7, v[80:81]
	v_lshl_add_u64 v[66:67], s[24:25], 0, v[66:67]
	s_waitcnt lgkmcnt(0)
	v_add_f32_e32 v64, v64, v65
	global_store_dword v[66:67], v64, off
; DEVINL float shx(float v, int m, int lane) { return __int_as_float(__builtin_amdgcn_ds_bpermute((lane ^ m) << 2, __float_as_int(v))); }
; DEVINL void phase_gemm_res(const Params& p, const u16* A, int lda, const u16* B, int K, const float* resid, char* smem, int wv) {
;     ...
; #pragma unroll
;     for (int ai = 0; ai < 2; ++ai)
; #pragma unroll
;       for (int m = 0; m < 4; ++m) {
;         int row = m0 + ai * 128 + wr * 64 + m * 16 + fr;
;         size_t off = (size_t)row * DM + n0 + wc * 32 + fq * 4;
;         size_t offw = (size_t)row * DM + n0 + wc * 32 + (fq & 1) * 16 + (fq >> 1) * 8;
;         float ss = 0.f;
; #pragma unroll
;         for (int bj = 0; bj < 2; ++bj) {
;           f32x4 vv[2];
; #pragma unroll
;           for (int n = 0; n < 2; ++n) {
;             float4 rv = *(const float4*)(resid + off + bj * 128 + n * 16);
;             f32x4 v = acc[ai][bj][m][n];
;             v[0] += rv.x; v[1] += rv.y; v[2] += rv.z; v[3] += rv.w;
;             float4 ov; ov.x = v[0]; ov.y = v[1]; ov.z = v[2]; ov.w = v[3];
;             *(float4*)(out + off + bj * 128 + n * 16) = ov;
;             ss += sumsq4(v);
;             vv[n] = v;
;           }
;           *(u32x4*)(xb + offw + bj * 128) = widen2(vv[0], vv[1]);
;         }
;         ss += shx(ss, 16, lane); ss += shx(ss, 32, lane);
;         if (fq == 0) part[(size_t)row * 32 + pn * 4 + wc] = ss;
;       }
.LBB0_1884:
	s_or_b64 exec, exec, s[28:29]
	v_add_u32_e32 v64, 0x80, v132
	s_waitcnt lgkmcnt(0)
	v_ashrrev_i32_e32 v65, 31, v64
	v_lshlrev_b64 v[66:67], 11, v[64:65]
	v_lshl_add_u64 v[74:75], v[66:67], 0, s[22:23]
	v_lshl_add_u64 v[66:67], v[74:75], 2, s[92:93]
	v_lshl_add_u64 v[76:77], v[66:67], 0, v[128:129]
	global_load_dwordx4 v[200:203], v[76:77], off
	global_load_dwordx4 v[204:207], v[76:77], off offset:64
	global_load_dwordx4 v[208:211], v[76:77], off offset:512
	global_load_dwordx4 v[212:215], v[76:77], off offset:576
	v_lshl_add_u64 v[74:75], v[74:75], 1, v[130:131]
	s_waitcnt vmcnt(3)
	v_pk_add_f32 v[60:61], v[60:61], v[200:201]
	v_pk_add_f32 v[62:63], v[62:63], v[202:203]
	s_waitcnt vmcnt(2)
	v_pk_add_f32 v[56:57], v[56:57], v[204:205]
	v_pk_add_f32 v[58:59], v[58:59], v[206:207]
	v_cvt_pk_bf16_f32 v66, v60, v61
	v_cvt_pk_bf16_f32 v67, v62, v63
	v_cvt_pk_bf16_f32 v68, v56, v57
	v_cvt_pk_bf16_f32 v69, v58, v59
	s_nop 0
	v_permlane16_swap_b32_e32 v66, v68
	v_permlane16_swap_b32_e32 v67, v69
	global_store_dwordx4 v[76:77], v[60:63], off
	global_store_dwordx4 v[76:77], v[56:59], off offset:64
	global_store_dwordx4 v[74:75], v[66:69], off
	s_nop 0
	v_pk_mul_f32 v[60:61], v[60:61], v[60:61]
	v_pk_mul_f32 v[56:57], v[56:57], v[56:57]
	v_pk_mul_f32 v[62:63], v[62:63], v[62:63]
	v_pk_mul_f32 v[58:59], v[58:59], v[58:59]
	v_add_f32_e32 v56, v56, v57
	v_add_f32_e32 v57, v60, v61
	v_add_f32_e32 v56, v58, v56
	v_add_f32_e32 v57, v62, v57
	v_add_f32_e32 v56, v59, v56
	v_add_f32_e32 v57, v63, v57
	v_add_f32_e32 v78, v57, v56
	s_waitcnt vmcnt(4)
	v_pk_add_f32 v[48:49], v[48:49], v[208:209]
	v_pk_add_f32 v[50:51], v[50:51], v[210:211]
	s_waitcnt vmcnt(3)
	v_pk_add_f32 v[52:53], v[52:53], v[212:213]
	v_pk_mul_f32 v[56:57], v[48:49], v[48:49]
	v_pk_add_f32 v[54:55], v[54:55], v[214:215]
	v_pk_mul_f32 v[58:59], v[50:51], v[50:51]
	v_pk_mul_f32 v[60:61], v[52:53], v[52:53]
	v_add_f32_e32 v56, v56, v57
	v_pk_mul_f32 v[62:63], v[54:55], v[54:55]
	v_add_f32_e32 v57, v60, v61
	v_add_f32_e32 v56, v58, v56
	v_add_f32_e32 v57, v62, v57
	v_add_f32_e32 v56, v59, v56
	v_add_f32_e32 v57, v63, v57
	v_add_f32_e32 v56, v78, v56
	v_add_f32_e32 v60, v56, v57
	ds_bpermute_b32 v61, v121, v60
	global_store_dwordx4 v[76:77], v[48:51], off offset:512
	v_cvt_pk_bf16_f32 v56, v48, v49
	v_cvt_pk_bf16_f32 v57, v50, v51
	v_cvt_pk_bf16_f32 v58, v52, v53
	s_waitcnt lgkmcnt(0)
	v_add_f32_e32 v48, v60, v61
	ds_bpermute_b32 v49, v120, v48
	v_cvt_pk_bf16_f32 v59, v54, v55
	v_permlane16_swap_b32_e32 v56, v58
	s_nop 0
	v_permlane16_swap_b32_e32 v57, v59
	global_store_dwordx4 v[76:77], v[52:55], off offset:576
	global_store_dwordx4 v[74:75], v[56:59], off offset:256
	s_and_saveexec_b64 s[28:29], vcc
	s_cbranch_execz .LBB0_1886
	v_lshlrev_b64 v[50:51], 7, v[64:65]
	v_lshl_add_u64 v[50:51], s[24:25], 0, v[50:51]
	s_waitcnt lgkmcnt(0)
	v_add_f32_e32 v48, v48, v49
	global_store_dword v[50:51], v48, off
.LBB0_1886:
	s_or_b64 exec, exec, s[28:29]
	v_add_u32_e32 v48, 0x90, v132
	s_waitcnt lgkmcnt(0)
	v_ashrrev_i32_e32 v49, 31, v48
	v_lshlrev_b64 v[50:51], 11, v[48:49]
	v_lshl_add_u64 v[58:59], v[50:51], 0, s[22:23]
	v_lshl_add_u64 v[50:51], v[58:59], 2, s[92:93]
	v_lshl_add_u64 v[60:61], v[50:51], 0, v[128:129]
	global_load_dwordx4 v[200:203], v[60:61], off
	global_load_dwordx4 v[204:207], v[60:61], off offset:64
	global_load_dwordx4 v[208:211], v[60:61], off offset:512
	global_load_dwordx4 v[212:215], v[60:61], off offset:576
	v_lshl_add_u64 v[58:59], v[58:59], 1, v[130:131]
	s_waitcnt vmcnt(3)
	v_pk_add_f32 v[44:45], v[44:45], v[200:201]
	v_pk_add_f32 v[46:47], v[46:47], v[202:203]
	s_waitcnt vmcnt(2)
	v_pk_add_f32 v[40:41], v[40:41], v[204:205]
	v_pk_add_f32 v[42:43], v[42:43], v[206:207]
	v_cvt_pk_bf16_f32 v50, v44, v45
	v_cvt_pk_bf16_f32 v51, v46, v47
	v_cvt_pk_bf16_f32 v52, v40, v41
	v_cvt_pk_bf16_f32 v53, v42, v43
	s_nop 0
	v_permlane16_swap_b32_e32 v50, v52
	v_permlane16_swap_b32_e32 v51, v53
	global_store_dwordx4 v[60:61], v[44:47], off
	global_store_dwordx4 v[60:61], v[40:43], off offset:64
	global_store_dwordx4 v[58:59], v[50:53], off
	s_nop 0
	v_pk_mul_f32 v[44:45], v[44:45], v[44:45]
	v_pk_mul_f32 v[40:41], v[40:41], v[40:41]
	v_pk_mul_f32 v[46:47], v[46:47], v[46:47]
	v_pk_mul_f32 v[42:43], v[42:43], v[42:43]
	v_add_f32_e32 v40, v40, v41
	v_add_f32_e32 v41, v44, v45
	v_add_f32_e32 v40, v42, v40
	v_add_f32_e32 v41, v46, v41
	v_add_f32_e32 v40, v43, v40
	v_add_f32_e32 v41, v47, v41
	v_add_f32_e32 v62, v41, v40
	s_waitcnt vmcnt(4)
	v_pk_add_f32 v[32:33], v[32:33], v[208:209]
	v_pk_add_f32 v[34:35], v[34:35], v[210:211]
	s_waitcnt vmcnt(3)
	v_pk_add_f32 v[36:37], v[36:37], v[212:213]
	v_pk_mul_f32 v[40:41], v[32:33], v[32:33]
	v_pk_add_f32 v[38:39], v[38:39], v[214:215]
	v_pk_mul_f32 v[42:43], v[34:35], v[34:35]
	v_pk_mul_f32 v[44:45], v[36:37], v[36:37]
	v_add_f32_e32 v40, v40, v41
	v_pk_mul_f32 v[46:47], v[38:39], v[38:39]
	v_add_f32_e32 v41, v44, v45
	v_add_f32_e32 v40, v42, v40
	v_add_f32_e32 v41, v46, v41
	v_add_f32_e32 v40, v43, v40
	v_add_f32_e32 v41, v47, v41
	v_add_f32_e32 v40, v62, v40
	v_add_f32_e32 v44, v40, v41
	ds_bpermute_b32 v45, v121, v44
	global_store_dwordx4 v[60:61], v[32:35], off offset:512
	v_cvt_pk_bf16_f32 v40, v32, v33
	v_cvt_pk_bf16_f32 v41, v34, v35
	v_cvt_pk_bf16_f32 v42, v36, v37
	s_waitcnt lgkmcnt(0)
	v_add_f32_e32 v32, v44, v45
	ds_bpermute_b32 v33, v120, v32
	v_cvt_pk_bf16_f32 v43, v38, v39
	v_permlane16_swap_b32_e32 v40, v42
	s_nop 0
	v_permlane16_swap_b32_e32 v41, v43
	global_store_dwordx4 v[60:61], v[36:39], off offset:576
	global_store_dwordx4 v[58:59], v[40:43], off offset:256
	s_and_saveexec_b64 s[28:29], vcc
	s_cbranch_execz .LBB0_1888
	v_lshlrev_b64 v[34:35], 7, v[48:49]
	v_lshl_add_u64 v[34:35], s[24:25], 0, v[34:35]
	s_waitcnt lgkmcnt(0)
	v_add_f32_e32 v32, v32, v33
	global_store_dword v[34:35], v32, off
; DEVINL float shx(float v, int m, int lane) { return __int_as_float(__builtin_amdgcn_ds_bpermute((lane ^ m) << 2, __float_as_int(v))); }
; DEVINL void phase_gemm_res(const Params& p, const u16* A, int lda, const u16* B, int K, const float* resid, char* smem, int wv) {
;     ...
; #pragma unroll
;     for (int ai = 0; ai < 2; ++ai)
; #pragma unroll
;       for (int m = 0; m < 4; ++m) {
;         int row = m0 + ai * 128 + wr * 64 + m * 16 + fr;
;         size_t off = (size_t)row * DM + n0 + wc * 32 + fq * 4;
;         size_t offw = (size_t)row * DM + n0 + wc * 32 + (fq & 1) * 16 + (fq >> 1) * 8;
;         float ss = 0.f;
; #pragma unroll
;         for (int bj = 0; bj < 2; ++bj) {
;           f32x4 vv[2];
; #pragma unroll
;           for (int n = 0; n < 2; ++n) {
;             float4 rv = *(const float4*)(resid + off + bj * 128 + n * 16);
;             f32x4 v = acc[ai][bj][m][n];
;             v[0] += rv.x; v[1] += rv.y; v[2] += rv.z; v[3] += rv.w;
;             float4 ov; ov.x = v[0]; ov.y = v[1]; ov.z = v[2]; ov.w = v[3];
;             *(float4*)(out + off + bj * 128 + n * 16) = ov;
;             ss += sumsq4(v);
;             vv[n] = v;
;           }
;           *(u32x4*)(xb + offw + bj * 128) = widen2(vv[0], vv[1]);
;         }
;         ss += shx(ss, 16, lane); ss += shx(ss, 32, lane);
;         if (fq == 0) part[(size_t)row * 32 + pn * 4 + wc] = ss;
;       }
.LBB0_1888:
	s_or_b64 exec, exec, s[28:29]
	v_add_u32_e32 v32, 0xa0, v132
	s_waitcnt lgkmcnt(0)
	v_ashrrev_i32_e32 v33, 31, v32
	v_lshlrev_b64 v[34:35], 11, v[32:33]
	v_lshl_add_u64 v[42:43], v[34:35], 0, s[22:23]
	v_lshl_add_u64 v[34:35], v[42:43], 2, s[92:93]
	v_lshl_add_u64 v[44:45], v[34:35], 0, v[128:129]
	global_load_dwordx4 v[200:203], v[44:45], off
	global_load_dwordx4 v[204:207], v[44:45], off offset:64
	global_load_dwordx4 v[208:211], v[44:45], off offset:512
	global_load_dwordx4 v[212:215], v[44:45], off offset:576
	v_lshl_add_u64 v[42:43], v[42:43], 1, v[130:131]
	s_waitcnt vmcnt(3)
	v_pk_add_f32 v[28:29], v[28:29], v[200:201]
	v_pk_add_f32 v[30:31], v[30:31], v[202:203]
	s_waitcnt vmcnt(2)
	v_pk_add_f32 v[24:25], v[24:25], v[204:205]
	v_pk_add_f32 v[26:27], v[26:27], v[206:207]
	v_cvt_pk_bf16_f32 v34, v28, v29
	v_cvt_pk_bf16_f32 v35, v30, v31
	v_cvt_pk_bf16_f32 v36, v24, v25
	v_cvt_pk_bf16_f32 v37, v26, v27
	s_nop 0
	v_permlane16_swap_b32_e32 v34, v36
	v_permlane16_swap_b32_e32 v35, v37
	global_store_dwordx4 v[44:45], v[28:31], off
	global_store_dwordx4 v[44:45], v[24:27], off offset:64
	global_store_dwordx4 v[42:43], v[34:37], off
	s_nop 0
	v_pk_mul_f32 v[28:29], v[28:29], v[28:29]
	v_pk_mul_f32 v[24:25], v[24:25], v[24:25]
	v_pk_mul_f32 v[30:31], v[30:31], v[30:31]
	v_pk_mul_f32 v[26:27], v[26:27], v[26:27]
	v_add_f32_e32 v24, v24, v25
	v_add_f32_e32 v25, v28, v29
	v_add_f32_e32 v24, v26, v24
	v_add_f32_e32 v25, v30, v25
	v_add_f32_e32 v24, v27, v24
	v_add_f32_e32 v25, v31, v25
	v_add_f32_e32 v46, v25, v24
	s_waitcnt vmcnt(4)
	v_pk_add_f32 v[16:17], v[16:17], v[208:209]
	v_pk_add_f32 v[18:19], v[18:19], v[210:211]
	s_waitcnt vmcnt(3)
	v_pk_add_f32 v[20:21], v[20:21], v[212:213]
	v_pk_mul_f32 v[24:25], v[16:17], v[16:17]
	v_pk_add_f32 v[22:23], v[22:23], v[214:215]
	v_pk_mul_f32 v[26:27], v[18:19], v[18:19]
	v_pk_mul_f32 v[28:29], v[20:21], v[20:21]
	v_add_f32_e32 v24, v24, v25
	v_pk_mul_f32 v[30:31], v[22:23], v[22:23]
	v_add_f32_e32 v25, v28, v29
	v_add_f32_e32 v24, v26, v24
	v_add_f32_e32 v25, v30, v25
	v_add_f32_e32 v24, v27, v24
	v_add_f32_e32 v25, v31, v25
	v_add_f32_e32 v24, v46, v24
	v_add_f32_e32 v28, v24, v25
	ds_bpermute_b32 v29, v121, v28
	global_store_dwordx4 v[44:45], v[16:19], off offset:512
	v_cvt_pk_bf16_f32 v24, v16, v17
	v_cvt_pk_bf16_f32 v25, v18, v19
	v_cvt_pk_bf16_f32 v26, v20, v21
	s_waitcnt lgkmcnt(0)
	v_add_f32_e32 v16, v28, v29
	ds_bpermute_b32 v17, v120, v16
	v_cvt_pk_bf16_f32 v27, v22, v23
	v_permlane16_swap_b32_e32 v24, v26
	s_nop 0
	v_permlane16_swap_b32_e32 v25, v27
	global_store_dwordx4 v[44:45], v[20:23], off offset:576
	global_store_dwordx4 v[42:43], v[24:27], off offset:256
	s_and_saveexec_b64 s[28:29], vcc
	s_cbranch_execz .LBB0_1890
	v_lshlrev_b64 v[18:19], 7, v[32:33]
	v_lshl_add_u64 v[18:19], s[24:25], 0, v[18:19]
	s_waitcnt lgkmcnt(0)
	v_add_f32_e32 v16, v16, v17
	global_store_dword v[18:19], v16, off
.LBB0_1890:
	s_or_b64 exec, exec, s[28:29]
	v_add_u32_e32 v16, 0xb0, v132
	s_waitcnt lgkmcnt(0)
	v_ashrrev_i32_e32 v17, 31, v16
	v_lshlrev_b64 v[18:19], 11, v[16:17]
	v_lshl_add_u64 v[26:27], v[18:19], 0, s[22:23]
	v_lshl_add_u64 v[18:19], v[26:27], 2, s[92:93]
	v_lshl_add_u64 v[28:29], v[18:19], 0, v[128:129]
	global_load_dwordx4 v[200:203], v[28:29], off
	global_load_dwordx4 v[204:207], v[28:29], off offset:64
	global_load_dwordx4 v[208:211], v[28:29], off offset:512
	global_load_dwordx4 v[212:215], v[28:29], off offset:576
	v_lshl_add_u64 v[26:27], v[26:27], 1, v[130:131]
	s_waitcnt vmcnt(3)
	v_pk_add_f32 v[12:13], v[12:13], v[200:201]
	v_pk_add_f32 v[14:15], v[14:15], v[202:203]
	s_waitcnt vmcnt(2)
	v_pk_add_f32 v[8:9], v[8:9], v[204:205]
	v_pk_add_f32 v[10:11], v[10:11], v[206:207]
	v_cvt_pk_bf16_f32 v18, v12, v13
	v_cvt_pk_bf16_f32 v19, v14, v15
	v_cvt_pk_bf16_f32 v20, v8, v9
	v_cvt_pk_bf16_f32 v21, v10, v11
	s_nop 0
	v_permlane16_swap_b32_e32 v18, v20
	v_permlane16_swap_b32_e32 v19, v21
	global_store_dwordx4 v[28:29], v[12:15], off
	global_store_dwordx4 v[28:29], v[8:11], off offset:64
	global_store_dwordx4 v[26:27], v[18:21], off
	s_nop 0
	v_pk_mul_f32 v[12:13], v[12:13], v[12:13]
	v_pk_mul_f32 v[8:9], v[8:9], v[8:9]
	v_pk_mul_f32 v[14:15], v[14:15], v[14:15]
	v_pk_mul_f32 v[10:11], v[10:11], v[10:11]
	v_add_f32_e32 v8, v8, v9
	v_add_f32_e32 v9, v12, v13
	v_add_f32_e32 v8, v10, v8
	v_add_f32_e32 v9, v14, v9
	v_add_f32_e32 v8, v11, v8
	v_add_f32_e32 v9, v15, v9
	v_add_f32_e32 v30, v9, v8
	s_waitcnt vmcnt(4)
	v_pk_add_f32 v[0:1], v[0:1], v[208:209]
	v_pk_add_f32 v[2:3], v[2:3], v[210:211]
	s_waitcnt vmcnt(3)
	v_pk_add_f32 v[4:5], v[4:5], v[212:213]
	v_pk_mul_f32 v[8:9], v[0:1], v[0:1]
	v_pk_add_f32 v[6:7], v[6:7], v[214:215]
	v_pk_mul_f32 v[10:11], v[2:3], v[2:3]
	v_pk_mul_f32 v[12:13], v[4:5], v[4:5]
	v_add_f32_e32 v8, v8, v9
	v_pk_mul_f32 v[14:15], v[6:7], v[6:7]
	v_add_f32_e32 v9, v12, v13
	v_add_f32_e32 v8, v10, v8
	v_add_f32_e32 v9, v14, v9
	v_add_f32_e32 v8, v11, v8
	v_add_f32_e32 v9, v15, v9
	v_add_f32_e32 v8, v30, v8
	v_add_f32_e32 v12, v8, v9
	ds_bpermute_b32 v13, v121, v12
	global_store_dwordx4 v[28:29], v[0:3], off offset:512
	v_cvt_pk_bf16_f32 v8, v0, v1
	v_cvt_pk_bf16_f32 v9, v2, v3
	v_cvt_pk_bf16_f32 v10, v4, v5
	s_waitcnt lgkmcnt(0)
	v_add_f32_e32 v0, v12, v13
	ds_bpermute_b32 v1, v120, v0
	v_cvt_pk_bf16_f32 v11, v6, v7
	v_permlane16_swap_b32_e32 v8, v10
	s_nop 0
	v_permlane16_swap_b32_e32 v9, v11
	global_store_dwordx4 v[28:29], v[4:7], off offset:576
	global_store_dwordx4 v[26:27], v[8:11], off offset:256
	s_and_saveexec_b64 s[22:23], vcc
	s_cbranch_execz .LBB0_1867
	v_lshlrev_b64 v[2:3], 7, v[16:17]
	v_lshl_add_u64 v[2:3], s[24:25], 0, v[2:3]
	s_waitcnt lgkmcnt(0)
	v_add_f32_e32 v0, v0, v1
	global_store_dword v[2:3], v0, off
	s_branch .LBB0_1867

; DEVINL float shx(float v, int m, int lane) { return __int_as_float(__builtin_amdgcn_ds_bpermute((lane ^ m) << 2, __float_as_int(v))); }
; DEVINL void phase_gemm_res(const Params& p, const u16* A, int lda, const u16* B, int K, const float* resid, char* smem, int wv) {
;     ...
; #pragma unroll
;     for (int ai = 0; ai < 2; ++ai)
; #pragma unroll
;       for (int m = 0; m < 4; ++m) {
;         int row = m0 + ai * 128 + wr * 64 + m * 16 + fr;
;         size_t off = (size_t)row * DM + n0 + wc * 32 + fq * 4;
;         size_t offw = (size_t)row * DM + n0 + wc * 32 + (fq & 1) * 16 + (fq >> 1) * 8;
;         float ss = 0.f;
; #pragma unroll
;         for (int bj = 0; bj < 2; ++bj) {
;           f32x4 vv[2];
; #pragma unroll
;           for (int n = 0; n < 2; ++n) {
;             float4 rv = *(const float4*)(resid + off + bj * 128 + n * 16);
;             f32x4 v = acc[ai][bj][m][n];
;             v[0] += rv.x; v[1] += rv.y; v[2] += rv.z; v[3] += rv.w;
;             float4 ov; ov.x = v[0]; ov.y = v[1]; ov.z = v[2]; ov.w = v[3];
;             *(float4*)(out + off + bj * 128 + n * 16) = ov;
;             ss += sumsq4(v);
;             vv[n] = v;
;           }
;           *(u32x4*)(xb + offw + bj * 128) = widen2(vv[0], vv[1]);
;         }
;         ss += shx(ss, 16, lane); ss += shx(ss, 32, lane);
;         if (fq == 0) part[(size_t)row * 32 + pn * 4 + wc] = ss;
;       }
.LBB0_1992:
	s_ashr_i32 s23, s27, 2
	s_andn2_b32 s23, s23, 63
	v_or_b32_e32 v128, s23, v128
	s_bfe_u32 s34, s27, 0x20006
	v_add_u32_e32 v132, s22, v128
	s_lshl_b32 s22, s34, 5
	v_lshrrev_b32_e32 v128, 2, v151
	v_and_b32_e32 v130, 16, v151
	v_ashrrev_i32_e32 v133, 31, v132
	s_or_b32 s20, s20, s22
	v_and_b32_e32 v136, 12, v128
	v_and_or_b32 v128, v128, 8, v130
	v_lshlrev_b64 v[134:135], 11, v[132:133]
	v_lshlrev_b32_e32 v128, 1, v128
	v_lshl_add_u64 v[142:143], v[134:135], 0, s[20:21]
	v_lshl_add_u64 v[130:131], s[90:91], 0, v[128:129]
	v_lshl_add_u64 v[134:135], v[142:143], 2, s[92:93]
	v_lshlrev_b32_e32 v128, 2, v136
	v_lshl_add_u64 v[146:147], v[134:135], 0, v[128:129]
	global_load_dwordx4 v[200:203], v[146:147], off
	global_load_dwordx4 v[204:207], v[146:147], off offset:64
	global_load_dwordx4 v[208:211], v[146:147], off offset:512
	global_load_dwordx4 v[212:215], v[146:147], off offset:576
	v_lshl_add_u64 v[148:149], v[142:143], 1, v[130:131]
	s_lshl_b32 s22, s26, 2
	s_ashr_i32 s23, s22, 31
	s_lshl_b64 s[22:23], s[22:23], 2
	s_add_u32 s22, s60, s22
	s_addc_u32 s23, s61, s23
	s_lshl_b32 s26, s34, 2
	s_add_u32 s22, s22, s26
	s_addc_u32 s23, s23, 0
	s_waitcnt vmcnt(2)
	v_pk_add_f32 v[124:125], v[124:125], v[200:201]
	v_pk_add_f32 v[126:127], v[126:127], v[202:203]
	v_pk_add_f32 v[134:135], v[120:121], v[204:205]
	v_pk_add_f32 v[136:137], v[122:123], v[206:207]
	v_cvt_pk_bf16_f32 v120, v124, v125
	v_cvt_pk_bf16_f32 v121, v126, v127
	v_cvt_pk_bf16_f32 v122, v134, v135
	v_cvt_pk_bf16_f32 v123, v136, v137
	s_nop 0
	v_permlane16_swap_b32_e32 v120, v122
	v_permlane16_swap_b32_e32 v121, v123
	global_store_dwordx4 v[146:147], v[124:127], off
	global_store_dwordx4 v[146:147], v[134:137], off offset:64
	global_store_dwordx4 v[148:149], v[120:123], off
	s_nop 1
	v_and_b32_e32 v120, 63, v151
	v_lshlrev_b32_e32 v122, 2, v120
	v_cmp_gt_u32_e32 vcc, 16, v120
	v_xor_b32_e32 v121, 64, v122
	v_xor_b32_e32 v120, 0x80, v122
	v_pk_mul_f32 v[122:123], v[124:125], v[124:125]
	v_pk_mul_f32 v[124:125], v[126:127], v[126:127]
	v_pk_mul_f32 v[126:127], v[134:135], v[134:135]
	v_pk_mul_f32 v[134:135], v[136:137], v[136:137]
	v_add_f32_e32 v126, v126, v127
	v_add_f32_e32 v122, v122, v123
	v_add_f32_e32 v123, v134, v126
	v_add_f32_e32 v122, v124, v122
	v_add_f32_e32 v123, v135, v123
	v_add_f32_e32 v122, v125, v122
	v_add_f32_e32 v136, v122, v123
	s_waitcnt vmcnt(3)
	v_pk_add_f32 v[112:113], v[112:113], v[208:209]
	v_pk_add_f32 v[114:115], v[114:115], v[210:211]
	v_pk_add_f32 v[116:117], v[116:117], v[212:213]
	v_pk_mul_f32 v[122:123], v[112:113], v[112:113]
	v_pk_add_f32 v[118:119], v[118:119], v[214:215]
	v_pk_mul_f32 v[124:125], v[114:115], v[114:115]
	v_pk_mul_f32 v[126:127], v[116:117], v[116:117]
	v_add_f32_e32 v122, v122, v123
	v_pk_mul_f32 v[134:135], v[118:119], v[118:119]
	v_add_f32_e32 v123, v126, v127
	v_add_f32_e32 v122, v124, v122
	v_add_f32_e32 v123, v134, v123
	v_add_f32_e32 v122, v125, v122
	v_add_f32_e32 v123, v135, v123
	v_add_f32_e32 v122, v136, v122
	v_add_f32_e32 v126, v122, v123
	ds_bpermute_b32 v127, v121, v126
	global_store_dwordx4 v[146:147], v[112:115], off offset:512
	v_cvt_pk_bf16_f32 v122, v112, v113
	v_cvt_pk_bf16_f32 v123, v114, v115
	v_cvt_pk_bf16_f32 v124, v116, v117
	s_waitcnt lgkmcnt(0)
	v_add_f32_e32 v112, v126, v127
	ds_bpermute_b32 v113, v120, v112
	v_cvt_pk_bf16_f32 v125, v118, v119
	v_permlane16_swap_b32_e32 v122, v124
	s_nop 0
	v_permlane16_swap_b32_e32 v123, v125
	global_store_dwordx4 v[146:147], v[116:119], off offset:576
	global_store_dwordx4 v[148:149], v[122:125], off offset:256
	s_and_saveexec_b64 s[26:27], vcc
	s_cbranch_execz .LBB0_1994
	v_lshlrev_b64 v[114:115], 7, v[132:133]
	v_lshl_add_u64 v[114:115], s[22:23], 0, v[114:115]
	s_waitcnt lgkmcnt(0)
	v_add_f32_e32 v112, v112, v113
	global_store_dword v[114:115], v112, off
.LBB0_1994:
	s_or_b64 exec, exec, s[26:27]
	v_or_b32_e32 v112, 16, v132
	s_waitcnt lgkmcnt(0)
	v_ashrrev_i32_e32 v113, 31, v112
	v_lshlrev_b64 v[114:115], 11, v[112:113]
	v_lshl_add_u64 v[118:119], v[114:115], 0, s[20:21]
	v_lshl_add_u64 v[114:115], v[118:119], 2, s[92:93]
	v_lshl_add_u64 v[126:127], v[114:115], 0, v[128:129]
	global_load_dwordx4 v[200:203], v[126:127], off
	global_load_dwordx4 v[204:207], v[126:127], off offset:64
	global_load_dwordx4 v[208:211], v[126:127], off offset:512
	global_load_dwordx4 v[212:215], v[126:127], off offset:576
	v_lshl_add_u64 v[118:119], v[118:119], 1, v[130:131]
	s_waitcnt vmcnt(3)
	v_pk_add_f32 v[108:109], v[108:109], v[200:201]
	v_pk_add_f32 v[110:111], v[110:111], v[202:203]
	s_waitcnt vmcnt(2)
	v_pk_add_f32 v[104:105], v[104:105], v[204:205]
	v_pk_add_f32 v[106:107], v[106:107], v[206:207]
	v_cvt_pk_bf16_f32 v114, v108, v109
	v_cvt_pk_bf16_f32 v115, v110, v111
	v_cvt_pk_bf16_f32 v116, v104, v105
	v_cvt_pk_bf16_f32 v117, v106, v107
	s_nop 0
	v_permlane16_swap_b32_e32 v114, v116
	v_permlane16_swap_b32_e32 v115, v117
	global_store_dwordx4 v[126:127], v[108:111], off
	global_store_dwordx4 v[126:127], v[104:107], off offset:64
	global_store_dwordx4 v[118:119], v[114:117], off
	s_nop 0
	v_pk_mul_f32 v[108:109], v[108:109], v[108:109]
	v_pk_mul_f32 v[104:105], v[104:105], v[104:105]
	v_pk_mul_f32 v[110:111], v[110:111], v[110:111]
	v_pk_mul_f32 v[106:107], v[106:107], v[106:107]
	v_add_f32_e32 v104, v104, v105
	v_add_f32_e32 v105, v108, v109
	v_add_f32_e32 v104, v106, v104
	v_add_f32_e32 v105, v110, v105
	v_add_f32_e32 v104, v107, v104
	v_add_f32_e32 v105, v111, v105
	v_add_f32_e32 v133, v105, v104
	s_waitcnt vmcnt(4)
	v_pk_add_f32 v[96:97], v[96:97], v[208:209]
	v_pk_add_f32 v[98:99], v[98:99], v[210:211]
	s_waitcnt vmcnt(3)
	v_pk_add_f32 v[100:101], v[100:101], v[212:213]
	v_pk_mul_f32 v[104:105], v[96:97], v[96:97]
	v_pk_add_f32 v[102:103], v[102:103], v[214:215]
	v_pk_mul_f32 v[106:107], v[98:99], v[98:99]
	v_pk_mul_f32 v[108:109], v[100:101], v[100:101]
	v_add_f32_e32 v104, v104, v105
	v_pk_mul_f32 v[110:111], v[102:103], v[102:103]
	v_add_f32_e32 v105, v108, v109
	v_add_f32_e32 v104, v106, v104
	v_add_f32_e32 v105, v110, v105
	v_add_f32_e32 v104, v107, v104
	v_add_f32_e32 v105, v111, v105
	v_add_f32_e32 v104, v133, v104
	v_add_f32_e32 v108, v104, v105
	ds_bpermute_b32 v109, v121, v108
	global_store_dwordx4 v[126:127], v[96:99], off offset:512
	v_cvt_pk_bf16_f32 v104, v96, v97
	v_cvt_pk_bf16_f32 v105, v98, v99
	v_cvt_pk_bf16_f32 v106, v100, v101
	s_waitcnt lgkmcnt(0)
	v_add_f32_e32 v96, v108, v109
	ds_bpermute_b32 v97, v120, v96
	v_cvt_pk_bf16_f32 v107, v102, v103
	v_permlane16_swap_b32_e32 v104, v106
	s_nop 0
	v_permlane16_swap_b32_e32 v105, v107
	global_store_dwordx4 v[126:127], v[100:103], off offset:576
	global_store_dwordx4 v[118:119], v[104:107], off offset:256
	s_and_saveexec_b64 s[26:27], vcc
	s_cbranch_execz .LBB0_1996
	v_lshlrev_b64 v[98:99], 7, v[112:113]
	v_lshl_add_u64 v[98:99], s[22:23], 0, v[98:99]
	s_waitcnt lgkmcnt(0)
	v_add_f32_e32 v96, v96, v97
	global_store_dword v[98:99], v96, off
; DEVINL float shx(float v, int m, int lane) { return __int_as_float(__builtin_amdgcn_ds_bpermute((lane ^ m) << 2, __float_as_int(v))); }
; DEVINL void phase_gemm_res(const Params& p, const u16* A, int lda, const u16* B, int K, const float* resid, char* smem, int wv) {
;     ...
; #pragma unroll
;     for (int ai = 0; ai < 2; ++ai)
; #pragma unroll
;       for (int m = 0; m < 4; ++m) {
;         int row = m0 + ai * 128 + wr * 64 + m * 16 + fr;
;         size_t off = (size_t)row * DM + n0 + wc * 32 + fq * 4;
;         size_t offw = (size_t)row * DM + n0 + wc * 32 + (fq & 1) * 16 + (fq >> 1) * 8;
;         float ss = 0.f;
; #pragma unroll
;         for (int bj = 0; bj < 2; ++bj) {
;           f32x4 vv[2];
; #pragma unroll
;           for (int n = 0; n < 2; ++n) {
;             float4 rv = *(const float4*)(resid + off + bj * 128 + n * 16);
;             f32x4 v = acc[ai][bj][m][n];
;             v[0] += rv.x; v[1] += rv.y; v[2] += rv.z; v[3] += rv.w;
;             float4 ov; ov.x = v[0]; ov.y = v[1]; ov.z = v[2]; ov.w = v[3];
;             *(float4*)(out + off + bj * 128 + n * 16) = ov;
;             ss += sumsq4(v);
;             vv[n] = v;
;           }
;           *(u32x4*)(xb + offw + bj * 128) = widen2(vv[0], vv[1]);
;         }
;         ss += shx(ss, 16, lane); ss += shx(ss, 32, lane);
;         if (fq == 0) part[(size_t)row * 32 + pn * 4 + wc] = ss;
;       }
.LBB0_1996:
	s_or_b64 exec, exec, s[26:27]
	v_or_b32_e32 v96, 32, v132
	s_waitcnt lgkmcnt(0)
	v_ashrrev_i32_e32 v97, 31, v96
	v_lshlrev_b64 v[98:99], 11, v[96:97]
	v_lshl_add_u64 v[106:107], v[98:99], 0, s[20:21]
	v_lshl_add_u64 v[98:99], v[106:107], 2, s[92:93]
	v_lshl_add_u64 v[108:109], v[98:99], 0, v[128:129]
	global_load_dwordx4 v[200:203], v[108:109], off
	global_load_dwordx4 v[204:207], v[108:109], off offset:64
	global_load_dwordx4 v[208:211], v[108:109], off offset:512
	global_load_dwordx4 v[212:215], v[108:109], off offset:576
	v_lshl_add_u64 v[106:107], v[106:107], 1, v[130:131]
	s_waitcnt vmcnt(3)
	v_pk_add_f32 v[92:93], v[92:93], v[200:201]
	v_pk_add_f32 v[94:95], v[94:95], v[202:203]
	s_waitcnt vmcnt(2)
	v_pk_add_f32 v[88:89], v[88:89], v[204:205]
	v_pk_add_f32 v[90:91], v[90:91], v[206:207]
	v_cvt_pk_bf16_f32 v98, v92, v93
	v_cvt_pk_bf16_f32 v99, v94, v95
	v_cvt_pk_bf16_f32 v100, v88, v89
	v_cvt_pk_bf16_f32 v101, v90, v91
	s_nop 0
	v_permlane16_swap_b32_e32 v98, v100
	v_permlane16_swap_b32_e32 v99, v101
	global_store_dwordx4 v[108:109], v[92:95], off
	global_store_dwordx4 v[108:109], v[88:91], off offset:64
	global_store_dwordx4 v[106:107], v[98:101], off
	s_nop 0
	v_pk_mul_f32 v[92:93], v[92:93], v[92:93]
	v_pk_mul_f32 v[88:89], v[88:89], v[88:89]
	v_pk_mul_f32 v[94:95], v[94:95], v[94:95]
	v_pk_mul_f32 v[90:91], v[90:91], v[90:91]
	v_add_f32_e32 v88, v88, v89
	v_add_f32_e32 v89, v92, v93
	v_add_f32_e32 v88, v90, v88
	v_add_f32_e32 v89, v94, v89
	v_add_f32_e32 v88, v91, v88
	v_add_f32_e32 v89, v95, v89
	v_add_f32_e32 v110, v89, v88
	s_waitcnt vmcnt(4)
	v_pk_add_f32 v[80:81], v[80:81], v[208:209]
	v_pk_add_f32 v[82:83], v[82:83], v[210:211]
	s_waitcnt vmcnt(3)
	v_pk_add_f32 v[84:85], v[84:85], v[212:213]
	v_pk_mul_f32 v[88:89], v[80:81], v[80:81]
	v_pk_add_f32 v[86:87], v[86:87], v[214:215]
	v_pk_mul_f32 v[90:91], v[82:83], v[82:83]
	v_pk_mul_f32 v[92:93], v[84:85], v[84:85]
	v_add_f32_e32 v88, v88, v89
	v_pk_mul_f32 v[94:95], v[86:87], v[86:87]
	v_add_f32_e32 v89, v92, v93
	v_add_f32_e32 v88, v90, v88
	v_add_f32_e32 v89, v94, v89
	v_add_f32_e32 v88, v91, v88
	v_add_f32_e32 v89, v95, v89
	v_add_f32_e32 v88, v110, v88
	v_add_f32_e32 v92, v88, v89
	ds_bpermute_b32 v93, v121, v92
	global_store_dwordx4 v[108:109], v[80:83], off offset:512
	v_cvt_pk_bf16_f32 v88, v80, v81
	v_cvt_pk_bf16_f32 v89, v82, v83
	v_cvt_pk_bf16_f32 v90, v84, v85
	s_waitcnt lgkmcnt(0)
	v_add_f32_e32 v80, v92, v93
	ds_bpermute_b32 v81, v120, v80
	v_cvt_pk_bf16_f32 v91, v86, v87
	v_permlane16_swap_b32_e32 v88, v90
	s_nop 0
	v_permlane16_swap_b32_e32 v89, v91
	global_store_dwordx4 v[108:109], v[84:87], off offset:576
	global_store_dwordx4 v[106:107], v[88:91], off offset:256
	s_and_saveexec_b64 s[26:27], vcc
	s_cbranch_execz .LBB0_1998
	v_lshlrev_b64 v[82:83], 7, v[96:97]
	v_lshl_add_u64 v[82:83], s[22:23], 0, v[82:83]
	s_waitcnt lgkmcnt(0)
	v_add_f32_e32 v80, v80, v81
	global_store_dword v[82:83], v80, off
.LBB0_1998:
	s_or_b64 exec, exec, s[26:27]
	v_or_b32_e32 v80, 48, v132
	s_waitcnt lgkmcnt(0)
	v_ashrrev_i32_e32 v81, 31, v80
	v_lshlrev_b64 v[82:83], 11, v[80:81]
	v_lshl_add_u64 v[90:91], v[82:83], 0, s[20:21]
	v_lshl_add_u64 v[82:83], v[90:91], 2, s[92:93]
	v_lshl_add_u64 v[92:93], v[82:83], 0, v[128:129]
	global_load_dwordx4 v[200:203], v[92:93], off
	global_load_dwordx4 v[204:207], v[92:93], off offset:64
	global_load_dwordx4 v[208:211], v[92:93], off offset:512
	global_load_dwordx4 v[212:215], v[92:93], off offset:576
	v_lshl_add_u64 v[90:91], v[90:91], 1, v[130:131]
	s_waitcnt vmcnt(3)
	v_pk_add_f32 v[76:77], v[76:77], v[200:201]
	v_pk_add_f32 v[78:79], v[78:79], v[202:203]
	s_waitcnt vmcnt(2)
	v_pk_add_f32 v[72:73], v[72:73], v[204:205]
	v_pk_add_f32 v[74:75], v[74:75], v[206:207]
	v_cvt_pk_bf16_f32 v82, v76, v77
	v_cvt_pk_bf16_f32 v83, v78, v79
	v_cvt_pk_bf16_f32 v84, v72, v73
	v_cvt_pk_bf16_f32 v85, v74, v75
	s_nop 0
	v_permlane16_swap_b32_e32 v82, v84
	v_permlane16_swap_b32_e32 v83, v85
	global_store_dwordx4 v[92:93], v[76:79], off
	global_store_dwordx4 v[92:93], v[72:75], off offset:64
	global_store_dwordx4 v[90:91], v[82:85], off
	s_nop 0
	v_pk_mul_f32 v[76:77], v[76:77], v[76:77]
	v_pk_mul_f32 v[72:73], v[72:73], v[72:73]
	v_pk_mul_f32 v[78:79], v[78:79], v[78:79]
	v_pk_mul_f32 v[74:75], v[74:75], v[74:75]
	v_add_f32_e32 v72, v72, v73
	v_add_f32_e32 v73, v76, v77
	v_add_f32_e32 v72, v74, v72
	v_add_f32_e32 v73, v78, v73
	v_add_f32_e32 v72, v75, v72
	v_add_f32_e32 v73, v79, v73
	v_add_f32_e32 v94, v73, v72
	s_waitcnt vmcnt(4)
	v_pk_add_f32 v[64:65], v[64:65], v[208:209]
	v_pk_add_f32 v[66:67], v[66:67], v[210:211]
	s_waitcnt vmcnt(3)
	v_pk_add_f32 v[68:69], v[68:69], v[212:213]
	v_pk_mul_f32 v[72:73], v[64:65], v[64:65]
	v_pk_add_f32 v[70:71], v[70:71], v[214:215]
	v_pk_mul_f32 v[74:75], v[66:67], v[66:67]
	v_pk_mul_f32 v[76:77], v[68:69], v[68:69]
	v_add_f32_e32 v72, v72, v73
	v_pk_mul_f32 v[78:79], v[70:71], v[70:71]
	v_add_f32_e32 v73, v76, v77
	v_add_f32_e32 v72, v74, v72
	v_add_f32_e32 v73, v78, v73
	v_add_f32_e32 v72, v75, v72
	v_add_f32_e32 v73, v79, v73
	v_add_f32_e32 v72, v94, v72
	v_add_f32_e32 v76, v72, v73
	ds_bpermute_b32 v77, v121, v76
	global_store_dwordx4 v[92:93], v[64:67], off offset:512
	v_cvt_pk_bf16_f32 v72, v64, v65
	v_cvt_pk_bf16_f32 v73, v66, v67
	v_cvt_pk_bf16_f32 v74, v68, v69
	s_waitcnt lgkmcnt(0)
	v_add_f32_e32 v64, v76, v77
	ds_bpermute_b32 v65, v120, v64
	v_cvt_pk_bf16_f32 v75, v70, v71
	v_permlane16_swap_b32_e32 v72, v74
	s_nop 0
	v_permlane16_swap_b32_e32 v73, v75
	global_store_dwordx4 v[92:93], v[68:71], off offset:576
	global_store_dwordx4 v[90:91], v[72:75], off offset:256
	s_and_saveexec_b64 s[26:27], vcc
	s_cbranch_execz .LBB0_2000
	v_lshlrev_b64 v[66:67], 7, v[80:81]
	v_lshl_add_u64 v[66:67], s[22:23], 0, v[66:67]
	s_waitcnt lgkmcnt(0)
	v_add_f32_e32 v64, v64, v65
	global_store_dword v[66:67], v64, off
; DEVINL float shx(float v, int m, int lane) { return __int_as_float(__builtin_amdgcn_ds_bpermute((lane ^ m) << 2, __float_as_int(v))); }
; DEVINL void phase_gemm_res(const Params& p, const u16* A, int lda, const u16* B, int K, const float* resid, char* smem, int wv) {
;     ...
; #pragma unroll
;     for (int ai = 0; ai < 2; ++ai)
; #pragma unroll
;       for (int m = 0; m < 4; ++m) {
;         int row = m0 + ai * 128 + wr * 64 + m * 16 + fr;
;         size_t off = (size_t)row * DM + n0 + wc * 32 + fq * 4;
;         size_t offw = (size_t)row * DM + n0 + wc * 32 + (fq & 1) * 16 + (fq >> 1) * 8;
;         float ss = 0.f;
; #pragma unroll
;         for (int bj = 0; bj < 2; ++bj) {
;           f32x4 vv[2];
; #pragma unroll
;           for (int n = 0; n < 2; ++n) {
;             float4 rv = *(const float4*)(resid + off + bj * 128 + n * 16);
;             f32x4 v = acc[ai][bj][m][n];
;             v[0] += rv.x; v[1] += rv.y; v[2] += rv.z; v[3] += rv.w;
;             float4 ov; ov.x = v[0]; ov.y = v[1]; ov.z = v[2]; ov.w = v[3];
;             *(float4*)(out + off + bj * 128 + n * 16) = ov;
;             ss += sumsq4(v);
;             vv[n] = v;
;           }
;           *(u32x4*)(xb + offw + bj * 128) = widen2(vv[0], vv[1]);
;         }
;         ss += shx(ss, 16, lane); ss += shx(ss, 32, lane);
;         if (fq == 0) part[(size_t)row * 32 + pn * 4 + wc] = ss;
;       }
.LBB0_2000:
	s_or_b64 exec, exec, s[26:27]
	v_add_u32_e32 v64, 0x80, v132
	s_waitcnt lgkmcnt(0)
	v_ashrrev_i32_e32 v65, 31, v64
	v_lshlrev_b64 v[66:67], 11, v[64:65]
	v_lshl_add_u64 v[74:75], v[66:67], 0, s[20:21]
	v_lshl_add_u64 v[66:67], v[74:75], 2, s[92:93]
	v_lshl_add_u64 v[76:77], v[66:67], 0, v[128:129]
	global_load_dwordx4 v[200:203], v[76:77], off
	global_load_dwordx4 v[204:207], v[76:77], off offset:64
	global_load_dwordx4 v[208:211], v[76:77], off offset:512
	global_load_dwordx4 v[212:215], v[76:77], off offset:576
	v_lshl_add_u64 v[74:75], v[74:75], 1, v[130:131]
	s_waitcnt vmcnt(3)
	v_pk_add_f32 v[60:61], v[60:61], v[200:201]
	v_pk_add_f32 v[62:63], v[62:63], v[202:203]
	s_waitcnt vmcnt(2)
	v_pk_add_f32 v[56:57], v[56:57], v[204:205]
	v_pk_add_f32 v[58:59], v[58:59], v[206:207]
	v_cvt_pk_bf16_f32 v66, v60, v61
	v_cvt_pk_bf16_f32 v67, v62, v63
	v_cvt_pk_bf16_f32 v68, v56, v57
	v_cvt_pk_bf16_f32 v69, v58, v59
	s_nop 0
	v_permlane16_swap_b32_e32 v66, v68
	v_permlane16_swap_b32_e32 v67, v69
	global_store_dwordx4 v[76:77], v[60:63], off
	global_store_dwordx4 v[76:77], v[56:59], off offset:64
	global_store_dwordx4 v[74:75], v[66:69], off
	s_nop 0
	v_pk_mul_f32 v[60:61], v[60:61], v[60:61]
	v_pk_mul_f32 v[56:57], v[56:57], v[56:57]
	v_pk_mul_f32 v[62:63], v[62:63], v[62:63]
	v_pk_mul_f32 v[58:59], v[58:59], v[58:59]
	v_add_f32_e32 v56, v56, v57
	v_add_f32_e32 v57, v60, v61
	v_add_f32_e32 v56, v58, v56
	v_add_f32_e32 v57, v62, v57
	v_add_f32_e32 v56, v59, v56
	v_add_f32_e32 v57, v63, v57
	v_add_f32_e32 v78, v57, v56
	s_waitcnt vmcnt(4)
	v_pk_add_f32 v[48:49], v[48:49], v[208:209]
	v_pk_add_f32 v[50:51], v[50:51], v[210:211]
	s_waitcnt vmcnt(3)
	v_pk_add_f32 v[52:53], v[52:53], v[212:213]
	v_pk_mul_f32 v[56:57], v[48:49], v[48:49]
	v_pk_add_f32 v[54:55], v[54:55], v[214:215]
	v_pk_mul_f32 v[58:59], v[50:51], v[50:51]
	v_pk_mul_f32 v[60:61], v[52:53], v[52:53]
	v_add_f32_e32 v56, v56, v57
	v_pk_mul_f32 v[62:63], v[54:55], v[54:55]
	v_add_f32_e32 v57, v60, v61
	v_add_f32_e32 v56, v58, v56
	v_add_f32_e32 v57, v62, v57
	v_add_f32_e32 v56, v59, v56
	v_add_f32_e32 v57, v63, v57
	v_add_f32_e32 v56, v78, v56
	v_add_f32_e32 v60, v56, v57
	ds_bpermute_b32 v61, v121, v60
	global_store_dwordx4 v[76:77], v[48:51], off offset:512
	v_cvt_pk_bf16_f32 v56, v48, v49
	v_cvt_pk_bf16_f32 v57, v50, v51
	v_cvt_pk_bf16_f32 v58, v52, v53
	s_waitcnt lgkmcnt(0)
	v_add_f32_e32 v48, v60, v61
	ds_bpermute_b32 v49, v120, v48
	v_cvt_pk_bf16_f32 v59, v54, v55
	v_permlane16_swap_b32_e32 v56, v58
	s_nop 0
	v_permlane16_swap_b32_e32 v57, v59
	global_store_dwordx4 v[76:77], v[52:55], off offset:576
	global_store_dwordx4 v[74:75], v[56:59], off offset:256
	s_and_saveexec_b64 s[26:27], vcc
	s_cbranch_execz .LBB0_2002
	v_lshlrev_b64 v[50:51], 7, v[64:65]
	v_lshl_add_u64 v[50:51], s[22:23], 0, v[50:51]
	s_waitcnt lgkmcnt(0)
	v_add_f32_e32 v48, v48, v49
	global_store_dword v[50:51], v48, off
.LBB0_2002:
	s_or_b64 exec, exec, s[26:27]
	v_add_u32_e32 v48, 0x90, v132
	s_waitcnt lgkmcnt(0)
	v_ashrrev_i32_e32 v49, 31, v48
	v_lshlrev_b64 v[50:51], 11, v[48:49]
	v_lshl_add_u64 v[58:59], v[50:51], 0, s[20:21]
	v_lshl_add_u64 v[50:51], v[58:59], 2, s[92:93]
	v_lshl_add_u64 v[60:61], v[50:51], 0, v[128:129]
	global_load_dwordx4 v[200:203], v[60:61], off
	global_load_dwordx4 v[204:207], v[60:61], off offset:64
	global_load_dwordx4 v[208:211], v[60:61], off offset:512
	global_load_dwordx4 v[212:215], v[60:61], off offset:576
	v_lshl_add_u64 v[58:59], v[58:59], 1, v[130:131]
	s_waitcnt vmcnt(3)
	v_pk_add_f32 v[44:45], v[44:45], v[200:201]
	v_pk_add_f32 v[46:47], v[46:47], v[202:203]
	s_waitcnt vmcnt(2)
	v_pk_add_f32 v[40:41], v[40:41], v[204:205]
	v_pk_add_f32 v[42:43], v[42:43], v[206:207]
	v_cvt_pk_bf16_f32 v50, v44, v45
	v_cvt_pk_bf16_f32 v51, v46, v47
	v_cvt_pk_bf16_f32 v52, v40, v41
	v_cvt_pk_bf16_f32 v53, v42, v43
	s_nop 0
	v_permlane16_swap_b32_e32 v50, v52
	v_permlane16_swap_b32_e32 v51, v53
	global_store_dwordx4 v[60:61], v[44:47], off
	global_store_dwordx4 v[60:61], v[40:43], off offset:64
	global_store_dwordx4 v[58:59], v[50:53], off
	s_nop 0
	v_pk_mul_f32 v[44:45], v[44:45], v[44:45]
	v_pk_mul_f32 v[40:41], v[40:41], v[40:41]
	v_pk_mul_f32 v[46:47], v[46:47], v[46:47]
	v_pk_mul_f32 v[42:43], v[42:43], v[42:43]
	v_add_f32_e32 v40, v40, v41
	v_add_f32_e32 v41, v44, v45
	v_add_f32_e32 v40, v42, v40
	v_add_f32_e32 v41, v46, v41
	v_add_f32_e32 v40, v43, v40
	v_add_f32_e32 v41, v47, v41
	v_add_f32_e32 v62, v41, v40
	s_waitcnt vmcnt(4)
	v_pk_add_f32 v[32:33], v[32:33], v[208:209]
	v_pk_add_f32 v[34:35], v[34:35], v[210:211]
	s_waitcnt vmcnt(3)
	v_pk_add_f32 v[36:37], v[36:37], v[212:213]
	v_pk_mul_f32 v[40:41], v[32:33], v[32:33]
	v_pk_add_f32 v[38:39], v[38:39], v[214:215]
	v_pk_mul_f32 v[42:43], v[34:35], v[34:35]
	v_pk_mul_f32 v[44:45], v[36:37], v[36:37]
	v_add_f32_e32 v40, v40, v41
	v_pk_mul_f32 v[46:47], v[38:39], v[38:39]
	v_add_f32_e32 v41, v44, v45
	v_add_f32_e32 v40, v42, v40
	v_add_f32_e32 v41, v46, v41
	v_add_f32_e32 v40, v43, v40
	v_add_f32_e32 v41, v47, v41
	v_add_f32_e32 v40, v62, v40
	v_add_f32_e32 v44, v40, v41
	ds_bpermute_b32 v45, v121, v44
	global_store_dwordx4 v[60:61], v[32:35], off offset:512
	v_cvt_pk_bf16_f32 v40, v32, v33
	v_cvt_pk_bf16_f32 v41, v34, v35
	v_cvt_pk_bf16_f32 v42, v36, v37
	s_waitcnt lgkmcnt(0)
	v_add_f32_e32 v32, v44, v45
	ds_bpermute_b32 v33, v120, v32
	v_cvt_pk_bf16_f32 v43, v38, v39
	v_permlane16_swap_b32_e32 v40, v42
	s_nop 0
	v_permlane16_swap_b32_e32 v41, v43
	global_store_dwordx4 v[60:61], v[36:39], off offset:576
	global_store_dwordx4 v[58:59], v[40:43], off offset:256
	s_and_saveexec_b64 s[26:27], vcc
	s_cbranch_execz .LBB0_2004
	v_lshlrev_b64 v[34:35], 7, v[48:49]
	v_lshl_add_u64 v[34:35], s[22:23], 0, v[34:35]
	s_waitcnt lgkmcnt(0)
	v_add_f32_e32 v32, v32, v33
	global_store_dword v[34:35], v32, off
; DEVINL float shx(float v, int m, int lane) { return __int_as_float(__builtin_amdgcn_ds_bpermute((lane ^ m) << 2, __float_as_int(v))); }
; DEVINL void phase_gemm_res(const Params& p, const u16* A, int lda, const u16* B, int K, const float* resid, char* smem, int wv) {
;     ...
; #pragma unroll
;     for (int ai = 0; ai < 2; ++ai)
; #pragma unroll
;       for (int m = 0; m < 4; ++m) {
;         int row = m0 + ai * 128 + wr * 64 + m * 16 + fr;
;         size_t off = (size_t)row * DM + n0 + wc * 32 + fq * 4;
;         size_t offw = (size_t)row * DM + n0 + wc * 32 + (fq & 1) * 16 + (fq >> 1) * 8;
;         float ss = 0.f;
; #pragma unroll
;         for (int bj = 0; bj < 2; ++bj) {
;           f32x4 vv[2];
; #pragma unroll
;           for (int n = 0; n < 2; ++n) {
;             float4 rv = *(const float4*)(resid + off + bj * 128 + n * 16);
;             f32x4 v = acc[ai][bj][m][n];
;             v[0] += rv.x; v[1] += rv.y; v[2] += rv.z; v[3] += rv.w;
;             float4 ov; ov.x = v[0]; ov.y = v[1]; ov.z = v[2]; ov.w = v[3];
;             *(float4*)(out + off + bj * 128 + n * 16) = ov;
;             ss += sumsq4(v);
;             vv[n] = v;
;           }
;           *(u32x4*)(xb + offw + bj * 128) = widen2(vv[0], vv[1]);
;         }
;         ss += shx(ss, 16, lane); ss += shx(ss, 32, lane);
;         if (fq == 0) part[(size_t)row * 32 + pn * 4 + wc] = ss;
;       }
.LBB0_2004:
	s_or_b64 exec, exec, s[26:27]
	v_add_u32_e32 v32, 0xa0, v132
	s_waitcnt lgkmcnt(0)
	v_ashrrev_i32_e32 v33, 31, v32
	v_lshlrev_b64 v[34:35], 11, v[32:33]
	v_lshl_add_u64 v[42:43], v[34:35], 0, s[20:21]
	v_lshl_add_u64 v[34:35], v[42:43], 2, s[92:93]
	v_lshl_add_u64 v[44:45], v[34:35], 0, v[128:129]
	global_load_dwordx4 v[200:203], v[44:45], off
	global_load_dwordx4 v[204:207], v[44:45], off offset:64
	global_load_dwordx4 v[208:211], v[44:45], off offset:512
	global_load_dwordx4 v[212:215], v[44:45], off offset:576
	v_lshl_add_u64 v[42:43], v[42:43], 1, v[130:131]
	s_waitcnt vmcnt(3)
	v_pk_add_f32 v[28:29], v[28:29], v[200:201]
	v_pk_add_f32 v[30:31], v[30:31], v[202:203]
	s_waitcnt vmcnt(2)
	v_pk_add_f32 v[24:25], v[24:25], v[204:205]
	v_pk_add_f32 v[26:27], v[26:27], v[206:207]
	v_cvt_pk_bf16_f32 v34, v28, v29
	v_cvt_pk_bf16_f32 v35, v30, v31
	v_cvt_pk_bf16_f32 v36, v24, v25
	v_cvt_pk_bf16_f32 v37, v26, v27
	s_nop 0
	v_permlane16_swap_b32_e32 v34, v36
	v_permlane16_swap_b32_e32 v35, v37
	global_store_dwordx4 v[44:45], v[28:31], off
	global_store_dwordx4 v[44:45], v[24:27], off offset:64
	global_store_dwordx4 v[42:43], v[34:37], off
	s_nop 0
	v_pk_mul_f32 v[28:29], v[28:29], v[28:29]
	v_pk_mul_f32 v[24:25], v[24:25], v[24:25]
	v_pk_mul_f32 v[30:31], v[30:31], v[30:31]
	v_pk_mul_f32 v[26:27], v[26:27], v[26:27]
	v_add_f32_e32 v24, v24, v25
	v_add_f32_e32 v25, v28, v29
	v_add_f32_e32 v24, v26, v24
	v_add_f32_e32 v25, v30, v25
	v_add_f32_e32 v24, v27, v24
	v_add_f32_e32 v25, v31, v25
	v_add_f32_e32 v46, v25, v24
	s_waitcnt vmcnt(4)
	v_pk_add_f32 v[16:17], v[16:17], v[208:209]
	v_pk_add_f32 v[18:19], v[18:19], v[210:211]
	s_waitcnt vmcnt(3)
	v_pk_add_f32 v[20:21], v[20:21], v[212:213]
	v_pk_mul_f32 v[24:25], v[16:17], v[16:17]
	v_pk_add_f32 v[22:23], v[22:23], v[214:215]
	v_pk_mul_f32 v[26:27], v[18:19], v[18:19]
	v_pk_mul_f32 v[28:29], v[20:21], v[20:21]
	v_add_f32_e32 v24, v24, v25
	v_pk_mul_f32 v[30:31], v[22:23], v[22:23]
	v_add_f32_e32 v25, v28, v29
	v_add_f32_e32 v24, v26, v24
	v_add_f32_e32 v25, v30, v25
	v_add_f32_e32 v24, v27, v24
	v_add_f32_e32 v25, v31, v25
	v_add_f32_e32 v24, v46, v24
	v_add_f32_e32 v28, v24, v25
	ds_bpermute_b32 v29, v121, v28
	global_store_dwordx4 v[44:45], v[16:19], off offset:512
	v_cvt_pk_bf16_f32 v24, v16, v17
	v_cvt_pk_bf16_f32 v25, v18, v19
	v_cvt_pk_bf16_f32 v26, v20, v21
	s_waitcnt lgkmcnt(0)
	v_add_f32_e32 v16, v28, v29
	ds_bpermute_b32 v17, v120, v16
	v_cvt_pk_bf16_f32 v27, v22, v23
	v_permlane16_swap_b32_e32 v24, v26
	s_nop 0
	v_permlane16_swap_b32_e32 v25, v27
	global_store_dwordx4 v[44:45], v[20:23], off offset:576
	global_store_dwordx4 v[42:43], v[24:27], off offset:256
	s_and_saveexec_b64 s[26:27], vcc
	s_cbranch_execz .LBB0_2006
	v_lshlrev_b64 v[18:19], 7, v[32:33]
	v_lshl_add_u64 v[18:19], s[22:23], 0, v[18:19]
	s_waitcnt lgkmcnt(0)
	v_add_f32_e32 v16, v16, v17
	global_store_dword v[18:19], v16, off
.LBB0_2006:
	s_or_b64 exec, exec, s[26:27]
	v_add_u32_e32 v16, 0xb0, v132
	s_waitcnt lgkmcnt(0)
	v_ashrrev_i32_e32 v17, 31, v16
	v_lshlrev_b64 v[18:19], 11, v[16:17]
	v_lshl_add_u64 v[26:27], v[18:19], 0, s[20:21]
	v_lshl_add_u64 v[18:19], v[26:27], 2, s[92:93]
	v_lshl_add_u64 v[28:29], v[18:19], 0, v[128:129]
	global_load_dwordx4 v[200:203], v[28:29], off
	global_load_dwordx4 v[204:207], v[28:29], off offset:64
	global_load_dwordx4 v[208:211], v[28:29], off offset:512
	global_load_dwordx4 v[212:215], v[28:29], off offset:576
	v_lshl_add_u64 v[26:27], v[26:27], 1, v[130:131]
	s_waitcnt vmcnt(3)
	v_pk_add_f32 v[12:13], v[12:13], v[200:201]
	v_pk_add_f32 v[14:15], v[14:15], v[202:203]
	s_waitcnt vmcnt(2)
	v_pk_add_f32 v[8:9], v[8:9], v[204:205]
	v_pk_add_f32 v[10:11], v[10:11], v[206:207]
	v_cvt_pk_bf16_f32 v18, v12, v13
	v_cvt_pk_bf16_f32 v19, v14, v15
	v_cvt_pk_bf16_f32 v20, v8, v9
	v_cvt_pk_bf16_f32 v21, v10, v11
	s_nop 0
	v_permlane16_swap_b32_e32 v18, v20
	v_permlane16_swap_b32_e32 v19, v21
	global_store_dwordx4 v[28:29], v[12:15], off
	global_store_dwordx4 v[28:29], v[8:11], off offset:64
	global_store_dwordx4 v[26:27], v[18:21], off
	s_nop 0
	v_pk_mul_f32 v[12:13], v[12:13], v[12:13]
	v_pk_mul_f32 v[8:9], v[8:9], v[8:9]
	v_pk_mul_f32 v[14:15], v[14:15], v[14:15]
	v_pk_mul_f32 v[10:11], v[10:11], v[10:11]
	v_add_f32_e32 v8, v8, v9
	v_add_f32_e32 v9, v12, v13
	v_add_f32_e32 v8, v10, v8
	v_add_f32_e32 v9, v14, v9
	v_add_f32_e32 v8, v11, v8
	v_add_f32_e32 v9, v15, v9
	v_add_f32_e32 v30, v9, v8
	s_waitcnt vmcnt(4)
	v_pk_add_f32 v[0:1], v[0:1], v[208:209]
	v_pk_add_f32 v[2:3], v[2:3], v[210:211]
	s_waitcnt vmcnt(3)
	v_pk_add_f32 v[4:5], v[4:5], v[212:213]
	v_pk_mul_f32 v[8:9], v[0:1], v[0:1]
	v_pk_add_f32 v[6:7], v[6:7], v[214:215]
	v_pk_mul_f32 v[10:11], v[2:3], v[2:3]
	v_pk_mul_f32 v[12:13], v[4:5], v[4:5]
	v_add_f32_e32 v8, v8, v9
	v_pk_mul_f32 v[14:15], v[6:7], v[6:7]
	v_add_f32_e32 v9, v12, v13
	v_add_f32_e32 v8, v10, v8
	v_add_f32_e32 v9, v14, v9
	v_add_f32_e32 v8, v11, v8
	v_add_f32_e32 v9, v15, v9
	v_add_f32_e32 v8, v30, v8
	v_add_f32_e32 v12, v8, v9
	ds_bpermute_b32 v13, v121, v12
	global_store_dwordx4 v[28:29], v[0:3], off offset:512
	v_cvt_pk_bf16_f32 v8, v0, v1
	v_cvt_pk_bf16_f32 v9, v2, v3
	v_cvt_pk_bf16_f32 v10, v4, v5
	s_waitcnt lgkmcnt(0)
	v_add_f32_e32 v0, v12, v13
	ds_bpermute_b32 v1, v120, v0
	v_cvt_pk_bf16_f32 v11, v6, v7
	v_permlane16_swap_b32_e32 v8, v10
	s_nop 0
	v_permlane16_swap_b32_e32 v9, v11
	global_store_dwordx4 v[28:29], v[4:7], off offset:576
	global_store_dwordx4 v[26:27], v[8:11], off offset:256
	s_and_saveexec_b64 s[20:21], vcc
	s_cbranch_execz .LBB0_1983
	v_lshlrev_b64 v[2:3], 7, v[16:17]
	v_lshl_add_u64 v[2:3], s[22:23], 0, v[2:3]
	s_waitcnt lgkmcnt(0)
	v_add_f32_e32 v0, v0, v1
	global_store_dword v[2:3], v0, off
	s_branch .LBB0_1983
